# GEMM loops: As[b][0] of K-tile t+3 issued after the K-pair's closing barrier (LDS-DMA pieces per load segment 4/4/4/4), waits unchanged
# speedup vs baseline: 1.0130x; 1.0074x over previous
.LBB0_152:
	ds_read_b128 v[128:131], v192
	ds_read_b128 v[132:135], v192 offset:1024
	ds_read_b128 v[136:139], v192 offset:2048
	ds_read_b128 v[140:143], v192 offset:3072
	ds_read_b128 v[164:167], v193
	ds_read_b128 v[168:171], v193 offset:1024
	ds_read_b128 v[172:175], v193 offset:2048
	ds_read_b128 v[176:179], v193 offset:3072
	s_add_u32 s78, s70, 0xfffc0080
	s_addc_u32 s79, s71, -1
	s_cmp_eq_u32 s96, 12
	s_cselect_b32 s81, s11, s79
	s_cselect_b32 s80, s22, s78
	s_cselect_b32 s79, s35, s95
	s_cselect_b32 s78, s37, s94
	v_lshl_add_u64 v[228:229], s[70:71], 0, v[156:157]
	s_add_i32 m0, s82, 0xc000
	ds_read_b128 v[196:199], v194
	ds_read_b128 v[200:203], v194 offset:1024
	ds_read_b128 v[204:207], v194 offset:2048
	ds_read_b128 v[208:211], v194 offset:3072
	ds_read_b128 v[212:215], v194 offset:4096
	ds_read_b128 v[216:219], v194 offset:5120
	ds_read_b128 v[220:223], v194 offset:6144
	ds_read_b128 v[224:227], v194 offset:7168
	global_load_lds_dwordx4 v[228:229], off
	v_lshl_add_u64 v[228:229], s[70:71], 0, v[158:159]
	s_add_i32 m0, s82, 0xe000
	s_nop 0
	global_load_lds_dwordx4 v[228:229], off
	s_waitcnt vmcnt(8)
	s_waitcnt lgkmcnt(0)
	s_barrier
	s_waitcnt lgkmcnt(0)
	v_mfma_f32_16x16x32_bf16 v[124:127], v[128:131], v[196:199], v[124:127]
	v_mfma_f32_16x16x32_bf16 v[120:123], v[136:139], v[196:199], v[120:123]
	v_mfma_f32_16x16x32_bf16 v[108:111], v[128:131], v[204:207], v[108:111]
	v_mfma_f32_16x16x32_bf16 v[104:107], v[136:139], v[204:207], v[104:107]
	v_mfma_f32_16x16x32_bf16 v[92:95], v[128:131], v[212:215], v[92:95]
	v_mfma_f32_16x16x32_bf16 v[88:91], v[136:139], v[212:215], v[88:91]
	v_mfma_f32_16x16x32_bf16 v[76:79], v[128:131], v[220:223], v[76:79]
	v_mfma_f32_16x16x32_bf16 v[72:75], v[136:139], v[220:223], v[72:75]
	v_mfma_f32_16x16x32_bf16 v[124:127], v[132:135], v[200:203], v[124:127]
	v_mfma_f32_16x16x32_bf16 v[120:123], v[140:143], v[200:203], v[120:123]
	v_mfma_f32_16x16x32_bf16 v[108:111], v[132:135], v[208:211], v[108:111]
	v_mfma_f32_16x16x32_bf16 v[104:107], v[140:143], v[208:211], v[104:107]
	v_mfma_f32_16x16x32_bf16 v[92:95], v[132:135], v[216:219], v[92:95]
	v_mfma_f32_16x16x32_bf16 v[88:91], v[140:143], v[216:219], v[88:91]
	v_mfma_f32_16x16x32_bf16 v[76:79], v[132:135], v[224:227], v[76:79]
	v_mfma_f32_16x16x32_bf16 v[72:75], v[140:143], v[224:227], v[72:75]
	v_mfma_f32_16x16x32_bf16 v[116:119], v[164:167], v[196:199], v[116:119]
	v_mfma_f32_16x16x32_bf16 v[112:115], v[172:175], v[196:199], v[112:115]
	v_mfma_f32_16x16x32_bf16 v[100:103], v[164:167], v[204:207], v[100:103]
	v_mfma_f32_16x16x32_bf16 v[96:99], v[172:175], v[204:207], v[96:99]
	v_mfma_f32_16x16x32_bf16 v[84:87], v[164:167], v[212:215], v[84:87]
	v_mfma_f32_16x16x32_bf16 v[80:83], v[172:175], v[212:215], v[80:83]
	v_mfma_f32_16x16x32_bf16 v[68:71], v[164:167], v[220:223], v[68:71]
	v_mfma_f32_16x16x32_bf16 v[64:67], v[172:175], v[220:223], v[64:67]
	v_mfma_f32_16x16x32_bf16 v[116:119], v[168:171], v[200:203], v[116:119]
	v_mfma_f32_16x16x32_bf16 v[112:115], v[176:179], v[200:203], v[112:115]
	v_mfma_f32_16x16x32_bf16 v[100:103], v[168:171], v[208:211], v[100:103]
	v_mfma_f32_16x16x32_bf16 v[96:99], v[176:179], v[208:211], v[96:99]
	v_mfma_f32_16x16x32_bf16 v[84:87], v[168:171], v[216:219], v[84:87]
	v_mfma_f32_16x16x32_bf16 v[80:83], v[176:179], v[216:219], v[80:83]
	v_mfma_f32_16x16x32_bf16 v[68:71], v[168:171], v[224:227], v[68:71]
	v_mfma_f32_16x16x32_bf16 v[64:67], v[176:179], v[224:227], v[64:67]
	s_barrier
	s_add_i32 s97, s90, s33
	v_lshl_add_u64 v[228:229], s[78:79], 0, v[146:147]
	s_mov_b32 m0, s97
	ds_read_b128 v[196:199], v194 offset:16384
	ds_read_b128 v[200:203], v194 offset:17408
	ds_read_b128 v[204:207], v194 offset:18432
	ds_read_b128 v[208:211], v194 offset:19456
	ds_read_b128 v[212:215], v194 offset:20480
	ds_read_b128 v[216:219], v194 offset:21504
	ds_read_b128 v[220:223], v194 offset:22528
	ds_read_b128 v[224:227], v194 offset:23552
	global_load_lds_dwordx4 v[228:229], off
	s_add_i32 m0, s97, 0x2000
	s_add_u32 vcc_lo, s78, 0x40000
	v_lshl_add_u64 v[230:231], s[78:79], 0, v[150:151]
	s_addc_u32 vcc_hi, s79, 0
	s_add_i32 s97, s91, s33
	global_load_lds_dwordx4 v[230:231], off
	v_lshl_add_u64 v[232:233], vcc, 0, v[146:147]
	s_mov_b32 m0, s97
	global_load_lds_dwordx4 v[232:233], off
	v_lshl_add_u64 v[232:233], vcc, 0, v[150:151]
	s_add_i32 m0, s97, 0x2000
	s_nop 0
	global_load_lds_dwordx4 v[232:233], off
	s_waitcnt vmcnt(6)
	s_waitcnt lgkmcnt(0)
	s_barrier
	s_waitcnt lgkmcnt(0)
	v_mfma_f32_16x16x32_bf16 v[60:63], v[128:131], v[196:199], v[60:63]
	v_mfma_f32_16x16x32_bf16 v[56:59], v[136:139], v[196:199], v[56:59]
	v_mfma_f32_16x16x32_bf16 v[44:47], v[128:131], v[204:207], v[44:47]
	v_mfma_f32_16x16x32_bf16 v[40:43], v[136:139], v[204:207], v[40:43]
	v_mfma_f32_16x16x32_bf16 v[28:31], v[128:131], v[212:215], v[28:31]
	v_mfma_f32_16x16x32_bf16 v[24:27], v[136:139], v[212:215], v[24:27]
	v_mfma_f32_16x16x32_bf16 v[12:15], v[128:131], v[220:223], v[12:15]
	v_mfma_f32_16x16x32_bf16 v[8:11], v[136:139], v[220:223], v[8:11]
	v_mfma_f32_16x16x32_bf16 v[60:63], v[132:135], v[200:203], v[60:63]
	v_mfma_f32_16x16x32_bf16 v[56:59], v[140:143], v[200:203], v[56:59]
	v_mfma_f32_16x16x32_bf16 v[44:47], v[132:135], v[208:211], v[44:47]
	v_mfma_f32_16x16x32_bf16 v[40:43], v[140:143], v[208:211], v[40:43]
	v_mfma_f32_16x16x32_bf16 v[28:31], v[132:135], v[216:219], v[28:31]
	v_mfma_f32_16x16x32_bf16 v[24:27], v[140:143], v[216:219], v[24:27]
	v_mfma_f32_16x16x32_bf16 v[12:15], v[132:135], v[224:227], v[12:15]
	v_mfma_f32_16x16x32_bf16 v[8:11], v[140:143], v[224:227], v[8:11]
	v_mfma_f32_16x16x32_bf16 v[52:55], v[164:167], v[196:199], v[52:55]
	v_mfma_f32_16x16x32_bf16 v[48:51], v[172:175], v[196:199], v[48:51]
	v_mfma_f32_16x16x32_bf16 v[36:39], v[164:167], v[204:207], v[36:39]
	v_mfma_f32_16x16x32_bf16 v[32:35], v[172:175], v[204:207], v[32:35]
	v_mfma_f32_16x16x32_bf16 v[20:23], v[164:167], v[212:215], v[20:23]
	v_mfma_f32_16x16x32_bf16 v[16:19], v[172:175], v[212:215], v[16:19]
	v_mfma_f32_16x16x32_bf16 v[4:7], v[164:167], v[220:223], v[4:7]
	v_mfma_f32_16x16x32_bf16 v[0:3], v[172:175], v[220:223], v[0:3]
	v_mfma_f32_16x16x32_bf16 v[52:55], v[168:171], v[200:203], v[52:55]
	v_mfma_f32_16x16x32_bf16 v[48:51], v[176:179], v[200:203], v[48:51]
	v_mfma_f32_16x16x32_bf16 v[36:39], v[168:171], v[208:211], v[36:39]
	v_mfma_f32_16x16x32_bf16 v[32:35], v[176:179], v[208:211], v[32:35]
	v_mfma_f32_16x16x32_bf16 v[20:23], v[168:171], v[216:219], v[20:23]
	v_mfma_f32_16x16x32_bf16 v[16:19], v[176:179], v[216:219], v[16:19]
	v_mfma_f32_16x16x32_bf16 v[4:7], v[168:171], v[224:227], v[4:7]
	v_mfma_f32_16x16x32_bf16 v[0:3], v[176:179], v[224:227], v[0:3]
	s_barrier
	s_add_i32 s97, 0, 0x18000
	s_add_i32 vcc_lo, 0, 0x1c000
	v_add_u32_e32 v140, s97, v180
	v_add_u32_e32 v152, vcc_lo, v180
	ds_read_b128 v[128:131], v140
	ds_read_b128 v[132:135], v140 offset:1024
	ds_read_b128 v[136:139], v140 offset:2048
	ds_read_b128 v[140:143], v140 offset:3072
	ds_read_b128 v[164:167], v152
	ds_read_b128 v[168:171], v152 offset:1024
	ds_read_b128 v[172:175], v152 offset:2048
	ds_read_b128 v[176:179], v152 offset:3072
	v_lshl_add_u64 v[232:233], s[80:81], 0, v[144:145]
	s_mov_b32 m0, s82
	v_lshl_add_u64 v[234:235], s[80:81], 0, v[148:149]
	global_load_lds_dwordx4 v[232:233], off
	s_mov_b32 m0, s83
	s_nop 0
	global_load_lds_dwordx4 v[234:235], off
	s_add_u32 s80, s80, 0x40000
	s_addc_u32 s81, s81, 0
	s_mov_b32 m0, s84
	v_lshl_add_u64 v[236:237], s[80:81], 0, v[144:145]
	ds_read_b128 v[196:199], v194 offset:32768
	ds_read_b128 v[200:203], v194 offset:33792
	ds_read_b128 v[204:207], v194 offset:34816
	ds_read_b128 v[208:211], v194 offset:35840
	ds_read_b128 v[212:215], v194 offset:36864
	ds_read_b128 v[216:219], v194 offset:37888
	ds_read_b128 v[220:223], v194 offset:38912
	ds_read_b128 v[224:227], v194 offset:39936
	global_load_lds_dwordx4 v[236:237], off
	v_lshl_add_u64 v[236:237], s[80:81], 0, v[148:149]
	s_mov_b32 m0, s85
	s_nop 0
	global_load_lds_dwordx4 v[236:237], off
	s_waitcnt vmcnt(8)
	s_waitcnt lgkmcnt(0)
	s_barrier
	s_waitcnt lgkmcnt(0)
	v_mfma_f32_16x16x32_bf16 v[124:127], v[128:131], v[196:199], v[124:127]
	v_mfma_f32_16x16x32_bf16 v[120:123], v[136:139], v[196:199], v[120:123]
	v_mfma_f32_16x16x32_bf16 v[108:111], v[128:131], v[204:207], v[108:111]
	v_mfma_f32_16x16x32_bf16 v[104:107], v[136:139], v[204:207], v[104:107]
	v_mfma_f32_16x16x32_bf16 v[92:95], v[128:131], v[212:215], v[92:95]
	v_mfma_f32_16x16x32_bf16 v[88:91], v[136:139], v[212:215], v[88:91]
	v_mfma_f32_16x16x32_bf16 v[76:79], v[128:131], v[220:223], v[76:79]
	v_mfma_f32_16x16x32_bf16 v[72:75], v[136:139], v[220:223], v[72:75]
	v_mfma_f32_16x16x32_bf16 v[124:127], v[132:135], v[200:203], v[124:127]
	v_mfma_f32_16x16x32_bf16 v[120:123], v[140:143], v[200:203], v[120:123]
	v_mfma_f32_16x16x32_bf16 v[108:111], v[132:135], v[208:211], v[108:111]
	v_mfma_f32_16x16x32_bf16 v[104:107], v[140:143], v[208:211], v[104:107]
	v_mfma_f32_16x16x32_bf16 v[92:95], v[132:135], v[216:219], v[92:95]
	v_mfma_f32_16x16x32_bf16 v[88:91], v[140:143], v[216:219], v[88:91]
	v_mfma_f32_16x16x32_bf16 v[76:79], v[132:135], v[224:227], v[76:79]
	v_mfma_f32_16x16x32_bf16 v[72:75], v[140:143], v[224:227], v[72:75]
	v_mfma_f32_16x16x32_bf16 v[116:119], v[164:167], v[196:199], v[116:119]
	v_mfma_f32_16x16x32_bf16 v[112:115], v[172:175], v[196:199], v[112:115]
	v_mfma_f32_16x16x32_bf16 v[100:103], v[164:167], v[204:207], v[100:103]
	v_mfma_f32_16x16x32_bf16 v[96:99], v[172:175], v[204:207], v[96:99]
	v_mfma_f32_16x16x32_bf16 v[84:87], v[164:167], v[212:215], v[84:87]
	v_mfma_f32_16x16x32_bf16 v[80:83], v[172:175], v[212:215], v[80:83]
	v_mfma_f32_16x16x32_bf16 v[68:71], v[164:167], v[220:223], v[68:71]
	v_mfma_f32_16x16x32_bf16 v[64:67], v[172:175], v[220:223], v[64:67]
	v_mfma_f32_16x16x32_bf16 v[116:119], v[168:171], v[200:203], v[116:119]
	v_mfma_f32_16x16x32_bf16 v[112:115], v[176:179], v[200:203], v[112:115]
	v_mfma_f32_16x16x32_bf16 v[100:103], v[168:171], v[208:211], v[100:103]
	v_mfma_f32_16x16x32_bf16 v[96:99], v[176:179], v[208:211], v[96:99]
	v_mfma_f32_16x16x32_bf16 v[84:87], v[168:171], v[216:219], v[84:87]
	v_mfma_f32_16x16x32_bf16 v[80:83], v[176:179], v[216:219], v[80:83]
	v_mfma_f32_16x16x32_bf16 v[68:71], v[168:171], v[224:227], v[68:71]
	v_mfma_f32_16x16x32_bf16 v[64:67], v[176:179], v[224:227], v[64:67]
	s_barrier
	s_add_i32 s80, s97, s33
	v_lshl_add_u64 v[228:229], v[228:229], 0, s[26:27]
	s_mov_b32 m0, s80
	ds_read_b128 v[196:199], v194 offset:49152
	ds_read_b128 v[200:203], v194 offset:50176
	ds_read_b128 v[204:207], v194 offset:51200
	ds_read_b128 v[208:211], v194 offset:52224
	ds_read_b128 v[212:215], v194 offset:53248
	ds_read_b128 v[216:219], v194 offset:54272
	ds_read_b128 v[220:223], v194 offset:55296
	ds_read_b128 v[224:227], v194 offset:56320
	global_load_lds_dwordx4 v[228:229], off
	s_add_i32 m0, s80, 0x2000
	s_add_u32 s78, s78, 0x40080
	v_lshl_add_u64 v[228:229], v[230:231], 0, s[26:27]
	s_addc_u32 s79, s79, 0
	s_add_i32 s80, vcc_lo, s33
	global_load_lds_dwordx4 v[228:229], off
	v_lshl_add_u64 v[228:229], s[78:79], 0, v[146:147]
	s_mov_b32 m0, s80
	s_nop 0
	global_load_lds_dwordx4 v[228:229], off
	v_lshl_add_u64 v[228:229], s[78:79], 0, v[150:151]
	s_add_i32 m0, s80, 0x2000
	s_nop 0
	global_load_lds_dwordx4 v[228:229], off
	s_waitcnt vmcnt(6)
	s_waitcnt lgkmcnt(0)
	s_barrier
	s_waitcnt lgkmcnt(0)
	v_mfma_f32_16x16x32_bf16 v[60:63], v[128:131], v[196:199], v[60:63]
	v_mfma_f32_16x16x32_bf16 v[56:59], v[136:139], v[196:199], v[56:59]
	v_mfma_f32_16x16x32_bf16 v[44:47], v[128:131], v[204:207], v[44:47]
	v_mfma_f32_16x16x32_bf16 v[40:43], v[136:139], v[204:207], v[40:43]
	v_mfma_f32_16x16x32_bf16 v[28:31], v[128:131], v[212:215], v[28:31]
	v_mfma_f32_16x16x32_bf16 v[24:27], v[136:139], v[212:215], v[24:27]
	v_mfma_f32_16x16x32_bf16 v[12:15], v[128:131], v[220:223], v[12:15]
	v_mfma_f32_16x16x32_bf16 v[8:11], v[136:139], v[220:223], v[8:11]
	v_mfma_f32_16x16x32_bf16 v[60:63], v[132:135], v[200:203], v[60:63]
	v_mfma_f32_16x16x32_bf16 v[56:59], v[140:143], v[200:203], v[56:59]
	v_mfma_f32_16x16x32_bf16 v[44:47], v[132:135], v[208:211], v[44:47]
	v_mfma_f32_16x16x32_bf16 v[40:43], v[140:143], v[208:211], v[40:43]
	v_mfma_f32_16x16x32_bf16 v[28:31], v[132:135], v[216:219], v[28:31]
	v_mfma_f32_16x16x32_bf16 v[24:27], v[140:143], v[216:219], v[24:27]
	v_mfma_f32_16x16x32_bf16 v[12:15], v[132:135], v[224:227], v[12:15]
	v_mfma_f32_16x16x32_bf16 v[8:11], v[140:143], v[224:227], v[8:11]
	v_mfma_f32_16x16x32_bf16 v[52:55], v[164:167], v[196:199], v[52:55]
	v_mfma_f32_16x16x32_bf16 v[48:51], v[172:175], v[196:199], v[48:51]
	v_mfma_f32_16x16x32_bf16 v[36:39], v[164:167], v[204:207], v[36:39]
	v_mfma_f32_16x16x32_bf16 v[32:35], v[172:175], v[204:207], v[32:35]
	v_mfma_f32_16x16x32_bf16 v[20:23], v[164:167], v[212:215], v[20:23]
	v_mfma_f32_16x16x32_bf16 v[16:19], v[172:175], v[212:215], v[16:19]
	v_mfma_f32_16x16x32_bf16 v[4:7], v[164:167], v[220:223], v[4:7]
	v_mfma_f32_16x16x32_bf16 v[0:3], v[172:175], v[220:223], v[0:3]
	v_mfma_f32_16x16x32_bf16 v[52:55], v[168:171], v[200:203], v[52:55]
	v_mfma_f32_16x16x32_bf16 v[48:51], v[176:179], v[200:203], v[48:51]
	v_mfma_f32_16x16x32_bf16 v[36:39], v[168:171], v[208:211], v[36:39]
	v_mfma_f32_16x16x32_bf16 v[32:35], v[176:179], v[208:211], v[32:35]
	v_mfma_f32_16x16x32_bf16 v[20:23], v[168:171], v[216:219], v[20:23]
	v_mfma_f32_16x16x32_bf16 v[16:19], v[176:179], v[216:219], v[16:19]
	v_mfma_f32_16x16x32_bf16 v[4:7], v[168:171], v[224:227], v[4:7]
	v_mfma_f32_16x16x32_bf16 v[0:3], v[176:179], v[224:227], v[0:3]
	s_barrier
	v_lshl_add_u64 v[228:229], v[232:233], 0, s[26:27]
	s_mov_b32 m0, s87
	s_nop 0
	global_load_lds_dwordx4 v[228:229], off
	v_lshl_add_u64 v[228:229], v[234:235], 0, s[26:27]
	s_mov_b32 m0, s88
	s_nop 0
	global_load_lds_dwordx4 v[228:229], off
	s_add_i32 s96, s96, 2
	s_add_u32 s70, s70, 0x100
	s_addc_u32 s71, s71, 0
	s_add_u32 s94, s94, 0x100
	s_addc_u32 s95, s95, 0
	s_cmp_gt_u32 s96, 13
	s_cbranch_scc0 .LBB0_152
	s_and_b64 vcc, exec, s[28:29]
	s_cbranch_vccz .LBB0_155
	s_barrier

.LBB0_617:
	ds_read_b128 v[144:147], v151
	ds_read_b128 v[156:159], v151 offset:1024
	ds_read_b128 v[160:163], v151 offset:2048
	ds_read_b128 v[164:167], v151 offset:3072
	ds_read_b128 v[168:171], v152
	ds_read_b128 v[172:175], v152 offset:1024
	ds_read_b128 v[176:179], v152 offset:2048
	ds_read_b128 v[184:187], v152 offset:3072
	s_add_u32 s26, s24, 0xfffc0080
	s_addc_u32 s27, s25, -1
	s_cmp_eq_u32 s51, 12
	s_cselect_b32 s29, s17, s27
	s_cselect_b32 s28, s23, s26
	s_cselect_b32 s27, s15, s50
	s_cselect_b32 s26, s46, s47
	v_lshl_add_u64 v[220:221], s[24:25], 0, v[136:137]
	s_add_i32 m0, s34, 0xc000
	ds_read_b128 v[188:191], v153
	ds_read_b128 v[192:195], v153 offset:1024
	ds_read_b128 v[196:199], v153 offset:2048
	ds_read_b128 v[200:203], v153 offset:3072
	ds_read_b128 v[204:207], v153 offset:4096
	ds_read_b128 v[208:211], v153 offset:5120
	ds_read_b128 v[212:215], v153 offset:6144
	ds_read_b128 v[216:219], v153 offset:7168
	global_load_lds_dwordx4 v[220:221], off
	v_lshl_add_u64 v[220:221], s[24:25], 0, v[138:139]
	s_add_i32 m0, s34, 0xe000
	s_nop 0
	global_load_lds_dwordx4 v[220:221], off
	s_waitcnt vmcnt(8)
	s_waitcnt lgkmcnt(0)
	s_barrier
	s_waitcnt lgkmcnt(0)
	v_mfma_f32_16x16x32_bf16 v[124:127], v[144:147], v[188:191], v[124:127]
	v_mfma_f32_16x16x32_bf16 v[120:123], v[160:163], v[188:191], v[120:123]
	v_mfma_f32_16x16x32_bf16 v[108:111], v[144:147], v[196:199], v[108:111]
	v_mfma_f32_16x16x32_bf16 v[104:107], v[160:163], v[196:199], v[104:107]
	v_mfma_f32_16x16x32_bf16 v[92:95], v[144:147], v[204:207], v[92:95]
	v_mfma_f32_16x16x32_bf16 v[88:91], v[160:163], v[204:207], v[88:91]
	v_mfma_f32_16x16x32_bf16 v[76:79], v[144:147], v[212:215], v[76:79]
	v_mfma_f32_16x16x32_bf16 v[72:75], v[160:163], v[212:215], v[72:75]
	v_mfma_f32_16x16x32_bf16 v[124:127], v[156:159], v[192:195], v[124:127]
	v_mfma_f32_16x16x32_bf16 v[120:123], v[164:167], v[192:195], v[120:123]
	v_mfma_f32_16x16x32_bf16 v[108:111], v[156:159], v[200:203], v[108:111]
	v_mfma_f32_16x16x32_bf16 v[104:107], v[164:167], v[200:203], v[104:107]
	v_mfma_f32_16x16x32_bf16 v[92:95], v[156:159], v[208:211], v[92:95]
	v_mfma_f32_16x16x32_bf16 v[88:91], v[164:167], v[208:211], v[88:91]
	v_mfma_f32_16x16x32_bf16 v[76:79], v[156:159], v[216:219], v[76:79]
	v_mfma_f32_16x16x32_bf16 v[72:75], v[164:167], v[216:219], v[72:75]
	v_mfma_f32_16x16x32_bf16 v[116:119], v[168:171], v[188:191], v[116:119]
	v_mfma_f32_16x16x32_bf16 v[112:115], v[176:179], v[188:191], v[112:115]
	v_mfma_f32_16x16x32_bf16 v[100:103], v[168:171], v[196:199], v[100:103]
	v_mfma_f32_16x16x32_bf16 v[96:99], v[176:179], v[196:199], v[96:99]
	v_mfma_f32_16x16x32_bf16 v[84:87], v[168:171], v[204:207], v[84:87]
	v_mfma_f32_16x16x32_bf16 v[80:83], v[176:179], v[204:207], v[80:83]
	v_mfma_f32_16x16x32_bf16 v[68:71], v[168:171], v[212:215], v[68:71]
	v_mfma_f32_16x16x32_bf16 v[64:67], v[176:179], v[212:215], v[64:67]
	v_mfma_f32_16x16x32_bf16 v[116:119], v[172:175], v[192:195], v[116:119]
	v_mfma_f32_16x16x32_bf16 v[112:115], v[184:187], v[192:195], v[112:115]
	v_mfma_f32_16x16x32_bf16 v[100:103], v[172:175], v[200:203], v[100:103]
	v_mfma_f32_16x16x32_bf16 v[96:99], v[184:187], v[200:203], v[96:99]
	v_mfma_f32_16x16x32_bf16 v[84:87], v[172:175], v[208:211], v[84:87]
	v_mfma_f32_16x16x32_bf16 v[80:83], v[184:187], v[208:211], v[80:83]
	v_mfma_f32_16x16x32_bf16 v[68:71], v[172:175], v[216:219], v[68:71]
	v_mfma_f32_16x16x32_bf16 v[64:67], v[184:187], v[216:219], v[64:67]
	s_barrier
	s_add_i32 s52, s41, s33
	v_lshl_add_u64 v[220:221], s[26:27], 0, v[130:131]
	s_mov_b32 m0, s52
	ds_read_b128 v[188:191], v153 offset:16384
	ds_read_b128 v[192:195], v153 offset:17408
	ds_read_b128 v[196:199], v153 offset:18432
	ds_read_b128 v[200:203], v153 offset:19456
	ds_read_b128 v[204:207], v153 offset:20480
	ds_read_b128 v[208:211], v153 offset:21504
	ds_read_b128 v[212:215], v153 offset:22528
	ds_read_b128 v[216:219], v153 offset:23552
	global_load_lds_dwordx4 v[220:221], off
	s_add_i32 m0, s52, 0x2000
	s_add_u32 s52, s26, 0x40000
	v_lshl_add_u64 v[222:223], s[26:27], 0, v[134:135]
	s_addc_u32 s53, s27, 0
	s_add_i32 s54, s42, s33
	global_load_lds_dwordx4 v[222:223], off
	v_lshl_add_u64 v[224:225], s[52:53], 0, v[130:131]
	s_mov_b32 m0, s54
	global_load_lds_dwordx4 v[224:225], off
	v_lshl_add_u64 v[224:225], s[52:53], 0, v[134:135]
	s_add_i32 m0, s54, 0x2000
	s_nop 0
	global_load_lds_dwordx4 v[224:225], off
	s_waitcnt vmcnt(6)
	s_waitcnt lgkmcnt(0)
	s_barrier
	s_waitcnt lgkmcnt(0)
	v_mfma_f32_16x16x32_bf16 v[60:63], v[144:147], v[188:191], v[60:63]
	v_mfma_f32_16x16x32_bf16 v[56:59], v[160:163], v[188:191], v[56:59]
	v_mfma_f32_16x16x32_bf16 v[44:47], v[144:147], v[196:199], v[44:47]
	v_mfma_f32_16x16x32_bf16 v[40:43], v[160:163], v[196:199], v[40:43]
	v_mfma_f32_16x16x32_bf16 v[28:31], v[144:147], v[204:207], v[28:31]
	v_mfma_f32_16x16x32_bf16 v[24:27], v[160:163], v[204:207], v[24:27]
	v_mfma_f32_16x16x32_bf16 v[12:15], v[144:147], v[212:215], v[12:15]
	v_mfma_f32_16x16x32_bf16 v[8:11], v[160:163], v[212:215], v[8:11]
	v_mfma_f32_16x16x32_bf16 v[60:63], v[156:159], v[192:195], v[60:63]
	v_mfma_f32_16x16x32_bf16 v[56:59], v[164:167], v[192:195], v[56:59]
	v_mfma_f32_16x16x32_bf16 v[44:47], v[156:159], v[200:203], v[44:47]
	v_mfma_f32_16x16x32_bf16 v[40:43], v[164:167], v[200:203], v[40:43]
	v_mfma_f32_16x16x32_bf16 v[28:31], v[156:159], v[208:211], v[28:31]
	v_mfma_f32_16x16x32_bf16 v[24:27], v[164:167], v[208:211], v[24:27]
	v_mfma_f32_16x16x32_bf16 v[12:15], v[156:159], v[216:219], v[12:15]
	v_mfma_f32_16x16x32_bf16 v[8:11], v[164:167], v[216:219], v[8:11]
	v_mfma_f32_16x16x32_bf16 v[52:55], v[168:171], v[188:191], v[52:55]
	v_mfma_f32_16x16x32_bf16 v[48:51], v[176:179], v[188:191], v[48:51]
	v_mfma_f32_16x16x32_bf16 v[36:39], v[168:171], v[196:199], v[36:39]
	v_mfma_f32_16x16x32_bf16 v[32:35], v[176:179], v[196:199], v[32:35]
	v_mfma_f32_16x16x32_bf16 v[20:23], v[168:171], v[204:207], v[20:23]
	v_mfma_f32_16x16x32_bf16 v[16:19], v[176:179], v[204:207], v[16:19]
	v_mfma_f32_16x16x32_bf16 v[4:7], v[168:171], v[212:215], v[4:7]
	v_mfma_f32_16x16x32_bf16 v[0:3], v[176:179], v[212:215], v[0:3]
	v_mfma_f32_16x16x32_bf16 v[52:55], v[172:175], v[192:195], v[52:55]
	v_mfma_f32_16x16x32_bf16 v[48:51], v[184:187], v[192:195], v[48:51]
	v_mfma_f32_16x16x32_bf16 v[36:39], v[172:175], v[200:203], v[36:39]
	v_mfma_f32_16x16x32_bf16 v[32:35], v[184:187], v[200:203], v[32:35]
	v_mfma_f32_16x16x32_bf16 v[20:23], v[172:175], v[208:211], v[20:23]
	v_mfma_f32_16x16x32_bf16 v[16:19], v[184:187], v[208:211], v[16:19]
	v_mfma_f32_16x16x32_bf16 v[4:7], v[172:175], v[216:219], v[4:7]
	v_mfma_f32_16x16x32_bf16 v[0:3], v[184:187], v[216:219], v[0:3]
	s_barrier
	s_add_i32 s52, 0, 0x18000
	v_add_u32_e32 v155, s52, v149
	s_add_i32 s53, 0, 0x1c000
	ds_read_b128 v[144:147], v155
	ds_read_b128 v[156:159], v155 offset:1024
	ds_read_b128 v[160:163], v155 offset:2048
	ds_read_b128 v[164:167], v155 offset:3072
	v_add_u32_e32 v155, s53, v149
	ds_read_b128 v[168:171], v155
	ds_read_b128 v[172:175], v155 offset:1024
	ds_read_b128 v[176:179], v155 offset:2048
	ds_read_b128 v[184:187], v155 offset:3072
	v_lshl_add_u64 v[224:225], s[28:29], 0, v[128:129]
	s_mov_b32 m0, s34
	v_lshl_add_u64 v[226:227], s[28:29], 0, v[132:133]
	global_load_lds_dwordx4 v[224:225], off
	s_mov_b32 m0, s35
	s_nop 0
	global_load_lds_dwordx4 v[226:227], off
	s_add_u32 s28, s28, 0x40000
	s_addc_u32 s29, s29, 0
	s_mov_b32 m0, s36
	v_lshl_add_u64 v[228:229], s[28:29], 0, v[128:129]
	ds_read_b128 v[188:191], v153 offset:32768
	ds_read_b128 v[192:195], v153 offset:33792
	ds_read_b128 v[196:199], v153 offset:34816
	ds_read_b128 v[200:203], v153 offset:35840
	ds_read_b128 v[204:207], v153 offset:36864
	ds_read_b128 v[208:211], v153 offset:37888
	ds_read_b128 v[212:215], v153 offset:38912
	ds_read_b128 v[216:219], v153 offset:39936
	global_load_lds_dwordx4 v[228:229], off
	v_lshl_add_u64 v[228:229], s[28:29], 0, v[132:133]
	s_mov_b32 m0, s37
	s_nop 0
	global_load_lds_dwordx4 v[228:229], off
	s_waitcnt vmcnt(8)
	s_waitcnt lgkmcnt(0)
	s_barrier
	s_waitcnt lgkmcnt(0)
	v_mfma_f32_16x16x32_bf16 v[124:127], v[144:147], v[188:191], v[124:127]
	v_mfma_f32_16x16x32_bf16 v[120:123], v[160:163], v[188:191], v[120:123]
	v_mfma_f32_16x16x32_bf16 v[108:111], v[144:147], v[196:199], v[108:111]
	v_mfma_f32_16x16x32_bf16 v[104:107], v[160:163], v[196:199], v[104:107]
	v_mfma_f32_16x16x32_bf16 v[92:95], v[144:147], v[204:207], v[92:95]
	v_mfma_f32_16x16x32_bf16 v[88:91], v[160:163], v[204:207], v[88:91]
	v_mfma_f32_16x16x32_bf16 v[76:79], v[144:147], v[212:215], v[76:79]
	v_mfma_f32_16x16x32_bf16 v[72:75], v[160:163], v[212:215], v[72:75]
	v_mfma_f32_16x16x32_bf16 v[124:127], v[156:159], v[192:195], v[124:127]
	v_mfma_f32_16x16x32_bf16 v[120:123], v[164:167], v[192:195], v[120:123]
	v_mfma_f32_16x16x32_bf16 v[108:111], v[156:159], v[200:203], v[108:111]
	v_mfma_f32_16x16x32_bf16 v[104:107], v[164:167], v[200:203], v[104:107]
	v_mfma_f32_16x16x32_bf16 v[92:95], v[156:159], v[208:211], v[92:95]
	v_mfma_f32_16x16x32_bf16 v[88:91], v[164:167], v[208:211], v[88:91]
	v_mfma_f32_16x16x32_bf16 v[76:79], v[156:159], v[216:219], v[76:79]
	v_mfma_f32_16x16x32_bf16 v[72:75], v[164:167], v[216:219], v[72:75]
	v_mfma_f32_16x16x32_bf16 v[116:119], v[168:171], v[188:191], v[116:119]
	v_mfma_f32_16x16x32_bf16 v[112:115], v[176:179], v[188:191], v[112:115]
	v_mfma_f32_16x16x32_bf16 v[100:103], v[168:171], v[196:199], v[100:103]
	v_mfma_f32_16x16x32_bf16 v[96:99], v[176:179], v[196:199], v[96:99]
	v_mfma_f32_16x16x32_bf16 v[84:87], v[168:171], v[204:207], v[84:87]
	v_mfma_f32_16x16x32_bf16 v[80:83], v[176:179], v[204:207], v[80:83]
	v_mfma_f32_16x16x32_bf16 v[68:71], v[168:171], v[212:215], v[68:71]
	v_mfma_f32_16x16x32_bf16 v[64:67], v[176:179], v[212:215], v[64:67]
	v_mfma_f32_16x16x32_bf16 v[116:119], v[172:175], v[192:195], v[116:119]
	v_mfma_f32_16x16x32_bf16 v[112:115], v[184:187], v[192:195], v[112:115]
	v_mfma_f32_16x16x32_bf16 v[100:103], v[172:175], v[200:203], v[100:103]
	v_mfma_f32_16x16x32_bf16 v[96:99], v[184:187], v[200:203], v[96:99]
	v_mfma_f32_16x16x32_bf16 v[84:87], v[172:175], v[208:211], v[84:87]
	v_mfma_f32_16x16x32_bf16 v[80:83], v[184:187], v[208:211], v[80:83]
	v_mfma_f32_16x16x32_bf16 v[68:71], v[172:175], v[216:219], v[68:71]
	v_mfma_f32_16x16x32_bf16 v[64:67], v[184:187], v[216:219], v[64:67]
	s_barrier
	s_add_i32 s28, s52, s33
	v_lshl_add_u64 v[220:221], v[220:221], 0, s[10:11]
	s_mov_b32 m0, s28
	ds_read_b128 v[188:191], v153 offset:49152
	ds_read_b128 v[192:195], v153 offset:50176
	ds_read_b128 v[196:199], v153 offset:51200
	ds_read_b128 v[200:203], v153 offset:52224
	ds_read_b128 v[204:207], v153 offset:53248
	ds_read_b128 v[208:211], v153 offset:54272
	ds_read_b128 v[212:215], v153 offset:55296
	ds_read_b128 v[216:219], v153 offset:56320
	global_load_lds_dwordx4 v[220:221], off
	s_add_i32 m0, s28, 0x2000
	s_add_u32 s26, s26, 0x40080
	v_lshl_add_u64 v[220:221], v[222:223], 0, s[10:11]
	s_addc_u32 s27, s27, 0
	s_add_i32 s28, s53, s33
	global_load_lds_dwordx4 v[220:221], off
	v_lshl_add_u64 v[220:221], s[26:27], 0, v[130:131]
	s_mov_b32 m0, s28
	s_nop 0
	global_load_lds_dwordx4 v[220:221], off
	v_lshl_add_u64 v[220:221], s[26:27], 0, v[134:135]
	s_add_i32 m0, s28, 0x2000
	s_nop 0
	global_load_lds_dwordx4 v[220:221], off
	s_waitcnt vmcnt(6)
	s_waitcnt lgkmcnt(0)
	s_barrier
	s_waitcnt lgkmcnt(0)
	v_mfma_f32_16x16x32_bf16 v[60:63], v[144:147], v[188:191], v[60:63]
	v_mfma_f32_16x16x32_bf16 v[56:59], v[160:163], v[188:191], v[56:59]
	v_mfma_f32_16x16x32_bf16 v[44:47], v[144:147], v[196:199], v[44:47]
	v_mfma_f32_16x16x32_bf16 v[40:43], v[160:163], v[196:199], v[40:43]
	v_mfma_f32_16x16x32_bf16 v[28:31], v[144:147], v[204:207], v[28:31]
	v_mfma_f32_16x16x32_bf16 v[24:27], v[160:163], v[204:207], v[24:27]
	v_mfma_f32_16x16x32_bf16 v[12:15], v[144:147], v[212:215], v[12:15]
	v_mfma_f32_16x16x32_bf16 v[8:11], v[160:163], v[212:215], v[8:11]
	v_mfma_f32_16x16x32_bf16 v[60:63], v[156:159], v[192:195], v[60:63]
	v_mfma_f32_16x16x32_bf16 v[56:59], v[164:167], v[192:195], v[56:59]
	v_mfma_f32_16x16x32_bf16 v[44:47], v[156:159], v[200:203], v[44:47]
	v_mfma_f32_16x16x32_bf16 v[40:43], v[164:167], v[200:203], v[40:43]
	v_mfma_f32_16x16x32_bf16 v[28:31], v[156:159], v[208:211], v[28:31]
	v_mfma_f32_16x16x32_bf16 v[24:27], v[164:167], v[208:211], v[24:27]
	v_mfma_f32_16x16x32_bf16 v[12:15], v[156:159], v[216:219], v[12:15]
	v_mfma_f32_16x16x32_bf16 v[8:11], v[164:167], v[216:219], v[8:11]
	v_mfma_f32_16x16x32_bf16 v[52:55], v[168:171], v[188:191], v[52:55]
	v_mfma_f32_16x16x32_bf16 v[48:51], v[176:179], v[188:191], v[48:51]
	v_mfma_f32_16x16x32_bf16 v[36:39], v[168:171], v[196:199], v[36:39]
	v_mfma_f32_16x16x32_bf16 v[32:35], v[176:179], v[196:199], v[32:35]
	v_mfma_f32_16x16x32_bf16 v[20:23], v[168:171], v[204:207], v[20:23]
	v_mfma_f32_16x16x32_bf16 v[16:19], v[176:179], v[204:207], v[16:19]
	v_mfma_f32_16x16x32_bf16 v[4:7], v[168:171], v[212:215], v[4:7]
	v_mfma_f32_16x16x32_bf16 v[0:3], v[176:179], v[212:215], v[0:3]
	v_mfma_f32_16x16x32_bf16 v[52:55], v[172:175], v[192:195], v[52:55]
	v_mfma_f32_16x16x32_bf16 v[48:51], v[184:187], v[192:195], v[48:51]
	v_mfma_f32_16x16x32_bf16 v[36:39], v[172:175], v[200:203], v[36:39]
	v_mfma_f32_16x16x32_bf16 v[32:35], v[184:187], v[200:203], v[32:35]
	v_mfma_f32_16x16x32_bf16 v[20:23], v[172:175], v[208:211], v[20:23]
	v_mfma_f32_16x16x32_bf16 v[16:19], v[184:187], v[208:211], v[16:19]
	v_mfma_f32_16x16x32_bf16 v[4:7], v[172:175], v[216:219], v[4:7]
	v_mfma_f32_16x16x32_bf16 v[0:3], v[184:187], v[216:219], v[0:3]
	s_barrier
	v_lshl_add_u64 v[220:221], v[224:225], 0, s[10:11]
	s_mov_b32 m0, s39
	s_nop 0
	global_load_lds_dwordx4 v[220:221], off
	v_lshl_add_u64 v[220:221], v[226:227], 0, s[10:11]
	s_mov_b32 m0, s40
	s_nop 0
	global_load_lds_dwordx4 v[220:221], off
	s_add_i32 s51, s51, 2
	s_add_u32 s24, s24, 0x100
	s_addc_u32 s25, s25, 0
	s_add_u32 s47, s47, 0x100
	s_addc_u32 s50, s50, 0
	s_cmp_gt_u32 s51, 13
	s_cbranch_scc0 .LBB0_617
	s_and_b64 vcc, exec, s[12:13]
	s_cbranch_vccz .LBB0_620
	s_barrier

.LBB0_705:
	ds_read_b128 v[154:157], v151
	ds_read_b128 v[158:161], v151 offset:1024
	ds_read_b128 v[162:165], v151 offset:2048
	ds_read_b128 v[166:169], v151 offset:3072
	ds_read_b128 v[170:173], v152
	ds_read_b128 v[174:177], v152 offset:1024
	ds_read_b128 v[184:187], v152 offset:2048
	ds_read_b128 v[188:191], v152 offset:3072
	s_add_u32 s22, s20, 0xfffc0080
	s_addc_u32 s23, s21, -1
	s_cmp_eq_u32 s50, 12
	s_cselect_b32 s25, s13, s23
	s_cselect_b32 s24, s42, s22
	s_cselect_b32 s23, s11, s47
	s_cselect_b32 s22, s43, s46
	v_lshl_add_u64 v[178:179], s[20:21], 0, v[136:137]
	s_add_i32 m0, s19, 0xc000
	ds_read_b128 v[192:195], v153
	ds_read_b128 v[196:199], v153 offset:1024
	ds_read_b128 v[200:203], v153 offset:2048
	ds_read_b128 v[204:207], v153 offset:3072
	ds_read_b128 v[208:211], v153 offset:4096
	ds_read_b128 v[212:215], v153 offset:5120
	ds_read_b128 v[216:219], v153 offset:6144
	ds_read_b128 v[220:223], v153 offset:7168
	global_load_lds_dwordx4 v[178:179], off
	v_lshl_add_u64 v[178:179], s[20:21], 0, v[138:139]
	s_add_i32 m0, s19, 0xe000
	s_nop 0
	global_load_lds_dwordx4 v[178:179], off
	s_waitcnt vmcnt(8)
	s_waitcnt lgkmcnt(0)
	s_barrier
	s_waitcnt lgkmcnt(0)
	v_mfma_f32_16x16x32_bf16 v[124:127], v[154:157], v[192:195], v[124:127]
	v_mfma_f32_16x16x32_bf16 v[116:119], v[162:165], v[192:195], v[116:119]
	v_mfma_f32_16x16x32_bf16 v[108:111], v[154:157], v[200:203], v[108:111]
	v_mfma_f32_16x16x32_bf16 v[100:103], v[162:165], v[200:203], v[100:103]
	v_mfma_f32_16x16x32_bf16 v[92:95], v[154:157], v[208:211], v[92:95]
	v_mfma_f32_16x16x32_bf16 v[84:87], v[162:165], v[208:211], v[84:87]
	v_mfma_f32_16x16x32_bf16 v[76:79], v[154:157], v[216:219], v[76:79]
	v_mfma_f32_16x16x32_bf16 v[68:71], v[162:165], v[216:219], v[68:71]
	v_mfma_f32_16x16x32_bf16 v[124:127], v[158:161], v[196:199], v[124:127]
	v_mfma_f32_16x16x32_bf16 v[116:119], v[166:169], v[196:199], v[116:119]
	v_mfma_f32_16x16x32_bf16 v[108:111], v[158:161], v[204:207], v[108:111]
	v_mfma_f32_16x16x32_bf16 v[100:103], v[166:169], v[204:207], v[100:103]
	v_mfma_f32_16x16x32_bf16 v[92:95], v[158:161], v[212:215], v[92:95]
	v_mfma_f32_16x16x32_bf16 v[84:87], v[166:169], v[212:215], v[84:87]
	v_mfma_f32_16x16x32_bf16 v[76:79], v[158:161], v[220:223], v[76:79]
	v_mfma_f32_16x16x32_bf16 v[68:71], v[166:169], v[220:223], v[68:71]
	v_mfma_f32_16x16x32_bf16 v[120:123], v[170:173], v[192:195], v[120:123]
	v_mfma_f32_16x16x32_bf16 v[112:115], v[184:187], v[192:195], v[112:115]
	v_mfma_f32_16x16x32_bf16 v[104:107], v[170:173], v[200:203], v[104:107]
	v_mfma_f32_16x16x32_bf16 v[96:99], v[184:187], v[200:203], v[96:99]
	v_mfma_f32_16x16x32_bf16 v[88:91], v[170:173], v[208:211], v[88:91]
	v_mfma_f32_16x16x32_bf16 v[80:83], v[184:187], v[208:211], v[80:83]
	v_mfma_f32_16x16x32_bf16 v[72:75], v[170:173], v[216:219], v[72:75]
	v_mfma_f32_16x16x32_bf16 v[64:67], v[184:187], v[216:219], v[64:67]
	v_mfma_f32_16x16x32_bf16 v[120:123], v[174:177], v[196:199], v[120:123]
	v_mfma_f32_16x16x32_bf16 v[112:115], v[188:191], v[196:199], v[112:115]
	v_mfma_f32_16x16x32_bf16 v[104:107], v[174:177], v[204:207], v[104:107]
	v_mfma_f32_16x16x32_bf16 v[96:99], v[188:191], v[204:207], v[96:99]
	v_mfma_f32_16x16x32_bf16 v[88:91], v[174:177], v[212:215], v[88:91]
	v_mfma_f32_16x16x32_bf16 v[80:83], v[188:191], v[212:215], v[80:83]
	v_mfma_f32_16x16x32_bf16 v[72:75], v[174:177], v[220:223], v[72:75]
	v_mfma_f32_16x16x32_bf16 v[64:67], v[188:191], v[220:223], v[64:67]
	s_barrier
	s_add_i32 s51, s36, s28
	v_lshl_add_u64 v[178:179], s[22:23], 0, v[132:133]
	s_mov_b32 m0, s51
	ds_read_b128 v[192:195], v153 offset:16384
	ds_read_b128 v[196:199], v153 offset:17408
	ds_read_b128 v[200:203], v153 offset:18432
	ds_read_b128 v[204:207], v153 offset:19456
	ds_read_b128 v[208:211], v153 offset:20480
	ds_read_b128 v[212:215], v153 offset:21504
	ds_read_b128 v[216:219], v153 offset:22528
	ds_read_b128 v[220:223], v153 offset:23552
	global_load_lds_dwordx4 v[178:179], off
	s_add_i32 m0, s51, 0x2000
	s_add_u32 s52, s22, 0x40000
	v_lshl_add_u64 v[224:225], s[22:23], 0, v[128:129]
	s_addc_u32 s53, s23, 0
	s_add_i32 s51, s37, s28
	global_load_lds_dwordx4 v[224:225], off
	v_lshl_add_u64 v[226:227], s[52:53], 0, v[132:133]
	s_mov_b32 m0, s51
	global_load_lds_dwordx4 v[226:227], off
	v_lshl_add_u64 v[226:227], s[52:53], 0, v[128:129]
	s_add_i32 m0, s51, 0x2000
	s_nop 0
	global_load_lds_dwordx4 v[226:227], off
	s_waitcnt vmcnt(6)
	s_waitcnt lgkmcnt(0)
	s_barrier
	s_waitcnt lgkmcnt(0)
	v_mfma_f32_16x16x32_bf16 v[60:63], v[154:157], v[192:195], v[60:63]
	v_mfma_f32_16x16x32_bf16 v[52:55], v[162:165], v[192:195], v[52:55]
	v_mfma_f32_16x16x32_bf16 v[44:47], v[154:157], v[200:203], v[44:47]
	v_mfma_f32_16x16x32_bf16 v[36:39], v[162:165], v[200:203], v[36:39]
	v_mfma_f32_16x16x32_bf16 v[28:31], v[154:157], v[208:211], v[28:31]
	v_mfma_f32_16x16x32_bf16 v[20:23], v[162:165], v[208:211], v[20:23]
	v_mfma_f32_16x16x32_bf16 v[12:15], v[154:157], v[216:219], v[12:15]
	v_mfma_f32_16x16x32_bf16 v[4:7], v[162:165], v[216:219], v[4:7]
	v_mfma_f32_16x16x32_bf16 v[60:63], v[158:161], v[196:199], v[60:63]
	v_mfma_f32_16x16x32_bf16 v[52:55], v[166:169], v[196:199], v[52:55]
	v_mfma_f32_16x16x32_bf16 v[44:47], v[158:161], v[204:207], v[44:47]
	v_mfma_f32_16x16x32_bf16 v[36:39], v[166:169], v[204:207], v[36:39]
	v_mfma_f32_16x16x32_bf16 v[28:31], v[158:161], v[212:215], v[28:31]
	v_mfma_f32_16x16x32_bf16 v[20:23], v[166:169], v[212:215], v[20:23]
	v_mfma_f32_16x16x32_bf16 v[12:15], v[158:161], v[220:223], v[12:15]
	v_mfma_f32_16x16x32_bf16 v[4:7], v[166:169], v[220:223], v[4:7]
	v_mfma_f32_16x16x32_bf16 v[56:59], v[170:173], v[192:195], v[56:59]
	v_mfma_f32_16x16x32_bf16 v[48:51], v[184:187], v[192:195], v[48:51]
	v_mfma_f32_16x16x32_bf16 v[40:43], v[170:173], v[200:203], v[40:43]
	v_mfma_f32_16x16x32_bf16 v[32:35], v[184:187], v[200:203], v[32:35]
	v_mfma_f32_16x16x32_bf16 v[24:27], v[170:173], v[208:211], v[24:27]
	v_mfma_f32_16x16x32_bf16 v[16:19], v[184:187], v[208:211], v[16:19]
	v_mfma_f32_16x16x32_bf16 v[8:11], v[170:173], v[216:219], v[8:11]
	v_mfma_f32_16x16x32_bf16 v[0:3], v[184:187], v[216:219], v[0:3]
	v_mfma_f32_16x16x32_bf16 v[56:59], v[174:177], v[196:199], v[56:59]
	v_mfma_f32_16x16x32_bf16 v[48:51], v[188:191], v[196:199], v[48:51]
	v_mfma_f32_16x16x32_bf16 v[40:43], v[174:177], v[204:207], v[40:43]
	v_mfma_f32_16x16x32_bf16 v[32:35], v[188:191], v[204:207], v[32:35]
	v_mfma_f32_16x16x32_bf16 v[24:27], v[174:177], v[212:215], v[24:27]
	v_mfma_f32_16x16x32_bf16 v[16:19], v[188:191], v[212:215], v[16:19]
	v_mfma_f32_16x16x32_bf16 v[8:11], v[174:177], v[220:223], v[8:11]
	v_mfma_f32_16x16x32_bf16 v[0:3], v[188:191], v[220:223], v[0:3]
	s_barrier
	s_add_i32 s51, 0, 0x18000
	s_add_i32 s52, 0, 0x1c000
	v_add_u32_e32 v166, s51, v145
	v_add_u32_e32 v180, s52, v145
	ds_read_b128 v[154:157], v166
	ds_read_b128 v[158:161], v166 offset:1024
	ds_read_b128 v[162:165], v166 offset:2048
	ds_read_b128 v[166:169], v166 offset:3072
	ds_read_b128 v[170:173], v180
	ds_read_b128 v[174:177], v180 offset:1024
	ds_read_b128 v[184:187], v180 offset:2048
	ds_read_b128 v[188:191], v180 offset:3072
	v_lshl_add_u64 v[226:227], s[24:25], 0, v[134:135]
	s_mov_b32 m0, s19
	v_lshl_add_u64 v[228:229], s[24:25], 0, v[130:131]
	global_load_lds_dwordx4 v[226:227], off
	s_mov_b32 m0, s30
	s_nop 0
	global_load_lds_dwordx4 v[228:229], off
	s_add_u32 s24, s24, 0x40000
	s_addc_u32 s25, s25, 0
	s_mov_b32 m0, s31
	v_lshl_add_u64 v[230:231], s[24:25], 0, v[134:135]
	ds_read_b128 v[192:195], v153 offset:32768
	ds_read_b128 v[196:199], v153 offset:33792
	ds_read_b128 v[200:203], v153 offset:34816
	ds_read_b128 v[204:207], v153 offset:35840
	ds_read_b128 v[208:211], v153 offset:36864
	ds_read_b128 v[212:215], v153 offset:37888
	ds_read_b128 v[216:219], v153 offset:38912
	ds_read_b128 v[220:223], v153 offset:39936
	global_load_lds_dwordx4 v[230:231], off
	v_lshl_add_u64 v[230:231], s[24:25], 0, v[130:131]
	s_mov_b32 m0, s33
	s_nop 0
	global_load_lds_dwordx4 v[230:231], off
	s_waitcnt vmcnt(8)
	s_waitcnt lgkmcnt(0)
	s_barrier
	s_waitcnt lgkmcnt(0)
	v_mfma_f32_16x16x32_bf16 v[124:127], v[154:157], v[192:195], v[124:127]
	v_mfma_f32_16x16x32_bf16 v[116:119], v[162:165], v[192:195], v[116:119]
	v_mfma_f32_16x16x32_bf16 v[108:111], v[154:157], v[200:203], v[108:111]
	v_mfma_f32_16x16x32_bf16 v[100:103], v[162:165], v[200:203], v[100:103]
	v_mfma_f32_16x16x32_bf16 v[92:95], v[154:157], v[208:211], v[92:95]
	v_mfma_f32_16x16x32_bf16 v[84:87], v[162:165], v[208:211], v[84:87]
	v_mfma_f32_16x16x32_bf16 v[76:79], v[154:157], v[216:219], v[76:79]
	v_mfma_f32_16x16x32_bf16 v[68:71], v[162:165], v[216:219], v[68:71]
	v_mfma_f32_16x16x32_bf16 v[124:127], v[158:161], v[196:199], v[124:127]
	v_mfma_f32_16x16x32_bf16 v[116:119], v[166:169], v[196:199], v[116:119]
	v_mfma_f32_16x16x32_bf16 v[108:111], v[158:161], v[204:207], v[108:111]
	v_mfma_f32_16x16x32_bf16 v[100:103], v[166:169], v[204:207], v[100:103]
	v_mfma_f32_16x16x32_bf16 v[92:95], v[158:161], v[212:215], v[92:95]
	v_mfma_f32_16x16x32_bf16 v[84:87], v[166:169], v[212:215], v[84:87]
	v_mfma_f32_16x16x32_bf16 v[76:79], v[158:161], v[220:223], v[76:79]
	v_mfma_f32_16x16x32_bf16 v[68:71], v[166:169], v[220:223], v[68:71]
	v_mfma_f32_16x16x32_bf16 v[120:123], v[170:173], v[192:195], v[120:123]
	v_mfma_f32_16x16x32_bf16 v[112:115], v[184:187], v[192:195], v[112:115]
	v_mfma_f32_16x16x32_bf16 v[104:107], v[170:173], v[200:203], v[104:107]
	v_mfma_f32_16x16x32_bf16 v[96:99], v[184:187], v[200:203], v[96:99]
	v_mfma_f32_16x16x32_bf16 v[88:91], v[170:173], v[208:211], v[88:91]
	v_mfma_f32_16x16x32_bf16 v[80:83], v[184:187], v[208:211], v[80:83]
	v_mfma_f32_16x16x32_bf16 v[72:75], v[170:173], v[216:219], v[72:75]
	v_mfma_f32_16x16x32_bf16 v[64:67], v[184:187], v[216:219], v[64:67]
	v_mfma_f32_16x16x32_bf16 v[120:123], v[174:177], v[196:199], v[120:123]
	v_mfma_f32_16x16x32_bf16 v[112:115], v[188:191], v[196:199], v[112:115]
	v_mfma_f32_16x16x32_bf16 v[104:107], v[174:177], v[204:207], v[104:107]
	v_mfma_f32_16x16x32_bf16 v[96:99], v[188:191], v[204:207], v[96:99]
	v_mfma_f32_16x16x32_bf16 v[88:91], v[174:177], v[212:215], v[88:91]
	v_mfma_f32_16x16x32_bf16 v[80:83], v[188:191], v[212:215], v[80:83]
	v_mfma_f32_16x16x32_bf16 v[72:75], v[174:177], v[220:223], v[72:75]
	v_mfma_f32_16x16x32_bf16 v[64:67], v[188:191], v[220:223], v[64:67]
	s_barrier
	s_add_i32 s24, s51, s28
	v_lshl_add_u64 v[178:179], v[178:179], 0, s[6:7]
	s_mov_b32 m0, s24
	ds_read_b128 v[192:195], v153 offset:49152
	ds_read_b128 v[196:199], v153 offset:50176
	ds_read_b128 v[200:203], v153 offset:51200
	ds_read_b128 v[204:207], v153 offset:52224
	ds_read_b128 v[208:211], v153 offset:53248
	ds_read_b128 v[212:215], v153 offset:54272
	ds_read_b128 v[216:219], v153 offset:55296
	ds_read_b128 v[220:223], v153 offset:56320
	global_load_lds_dwordx4 v[178:179], off
	s_add_i32 m0, s24, 0x2000
	s_add_u32 s22, s22, 0x40080
	v_lshl_add_u64 v[178:179], v[224:225], 0, s[6:7]
	s_addc_u32 s23, s23, 0
	s_add_i32 s24, s52, s28
	global_load_lds_dwordx4 v[178:179], off
	v_lshl_add_u64 v[178:179], s[22:23], 0, v[132:133]
	s_mov_b32 m0, s24
	s_nop 0
	global_load_lds_dwordx4 v[178:179], off
	v_lshl_add_u64 v[178:179], s[22:23], 0, v[128:129]
	s_add_i32 m0, s24, 0x2000
	s_nop 0
	global_load_lds_dwordx4 v[178:179], off
	s_waitcnt vmcnt(6)
	s_waitcnt lgkmcnt(0)
	s_barrier
	s_waitcnt lgkmcnt(0)
	v_mfma_f32_16x16x32_bf16 v[60:63], v[154:157], v[192:195], v[60:63]
	v_mfma_f32_16x16x32_bf16 v[52:55], v[162:165], v[192:195], v[52:55]
	v_mfma_f32_16x16x32_bf16 v[44:47], v[154:157], v[200:203], v[44:47]
	v_mfma_f32_16x16x32_bf16 v[36:39], v[162:165], v[200:203], v[36:39]
	v_mfma_f32_16x16x32_bf16 v[28:31], v[154:157], v[208:211], v[28:31]
	v_mfma_f32_16x16x32_bf16 v[20:23], v[162:165], v[208:211], v[20:23]
	v_mfma_f32_16x16x32_bf16 v[12:15], v[154:157], v[216:219], v[12:15]
	v_mfma_f32_16x16x32_bf16 v[4:7], v[162:165], v[216:219], v[4:7]
	v_mfma_f32_16x16x32_bf16 v[60:63], v[158:161], v[196:199], v[60:63]
	v_mfma_f32_16x16x32_bf16 v[52:55], v[166:169], v[196:199], v[52:55]
	v_mfma_f32_16x16x32_bf16 v[44:47], v[158:161], v[204:207], v[44:47]
	v_mfma_f32_16x16x32_bf16 v[36:39], v[166:169], v[204:207], v[36:39]
	v_mfma_f32_16x16x32_bf16 v[28:31], v[158:161], v[212:215], v[28:31]
	v_mfma_f32_16x16x32_bf16 v[20:23], v[166:169], v[212:215], v[20:23]
	v_mfma_f32_16x16x32_bf16 v[12:15], v[158:161], v[220:223], v[12:15]
	v_mfma_f32_16x16x32_bf16 v[4:7], v[166:169], v[220:223], v[4:7]
	v_mfma_f32_16x16x32_bf16 v[56:59], v[170:173], v[192:195], v[56:59]
	v_mfma_f32_16x16x32_bf16 v[48:51], v[184:187], v[192:195], v[48:51]
	v_mfma_f32_16x16x32_bf16 v[40:43], v[170:173], v[200:203], v[40:43]
	v_mfma_f32_16x16x32_bf16 v[32:35], v[184:187], v[200:203], v[32:35]
	v_mfma_f32_16x16x32_bf16 v[24:27], v[170:173], v[208:211], v[24:27]
	v_mfma_f32_16x16x32_bf16 v[16:19], v[184:187], v[208:211], v[16:19]
	v_mfma_f32_16x16x32_bf16 v[8:11], v[170:173], v[216:219], v[8:11]
	v_mfma_f32_16x16x32_bf16 v[0:3], v[184:187], v[216:219], v[0:3]
	v_mfma_f32_16x16x32_bf16 v[56:59], v[174:177], v[196:199], v[56:59]
	v_mfma_f32_16x16x32_bf16 v[48:51], v[188:191], v[196:199], v[48:51]
	v_mfma_f32_16x16x32_bf16 v[40:43], v[174:177], v[204:207], v[40:43]
	v_mfma_f32_16x16x32_bf16 v[32:35], v[188:191], v[204:207], v[32:35]
	v_mfma_f32_16x16x32_bf16 v[24:27], v[174:177], v[212:215], v[24:27]
	v_mfma_f32_16x16x32_bf16 v[16:19], v[188:191], v[212:215], v[16:19]
	v_mfma_f32_16x16x32_bf16 v[8:11], v[174:177], v[220:223], v[8:11]
	v_mfma_f32_16x16x32_bf16 v[0:3], v[188:191], v[220:223], v[0:3]
	s_barrier
	v_lshl_add_u64 v[178:179], v[226:227], 0, s[6:7]
	s_mov_b32 m0, s34
	s_nop 0
	global_load_lds_dwordx4 v[178:179], off
	v_lshl_add_u64 v[178:179], v[228:229], 0, s[6:7]
	s_mov_b32 m0, s35
	s_nop 0
	global_load_lds_dwordx4 v[178:179], off
	s_add_i32 s50, s50, 2
	s_add_u32 s20, s20, 0x100
	s_addc_u32 s21, s21, 0
	s_add_u32 s46, s46, 0x100
	s_addc_u32 s47, s47, 0
	s_cmp_gt_u32 s50, 13
	s_cbranch_scc0 .LBB0_705
	s_and_b64 vcc, exec, s[8:9]
	s_cbranch_vccz .LBB0_708
	s_barrier

.LBB0_787:
	ds_read_b128 v[144:147], v151
	ds_read_b128 v[156:159], v151 offset:1024
	ds_read_b128 v[160:163], v151 offset:2048
	ds_read_b128 v[164:167], v151 offset:3072
	ds_read_b128 v[168:171], v152
	ds_read_b128 v[172:175], v152 offset:1024
	ds_read_b128 v[176:179], v152 offset:2048
	ds_read_b128 v[184:187], v152 offset:3072
	s_add_u32 s20, s18, 0x100
	s_addc_u32 s21, s19, 0
	s_cmp_eq_u32 s47, 40
	s_cselect_b32 s25, s7, s21
	s_cselect_b32 s24, s6, s20
	s_cselect_b32 s23, s17, s46
	s_cselect_b32 s22, s16, s43
	v_lshl_add_u64 v[220:221], s[18:19], 0, v[136:137]
	s_add_i32 m0, s29, 0xc000
	ds_read_b128 v[188:191], v153
	ds_read_b128 v[192:195], v153 offset:1024
	ds_read_b128 v[196:199], v153 offset:2048
	ds_read_b128 v[200:203], v153 offset:3072
	ds_read_b128 v[204:207], v153 offset:4096
	ds_read_b128 v[208:211], v153 offset:5120
	ds_read_b128 v[212:215], v153 offset:6144
	ds_read_b128 v[216:219], v153 offset:7168
	global_load_lds_dwordx4 v[220:221], off
	v_lshl_add_u64 v[220:221], s[18:19], 0, v[138:139]
	s_add_i32 m0, s29, 0xe000
	s_nop 0
	global_load_lds_dwordx4 v[220:221], off
	s_waitcnt vmcnt(8)
	s_waitcnt lgkmcnt(0)
	s_barrier
	s_waitcnt lgkmcnt(0)
	v_mfma_f32_16x16x32_bf16 v[124:127], v[144:147], v[188:191], v[124:127]
	v_mfma_f32_16x16x32_bf16 v[120:123], v[160:163], v[188:191], v[120:123]
	v_mfma_f32_16x16x32_bf16 v[108:111], v[144:147], v[196:199], v[108:111]
	v_mfma_f32_16x16x32_bf16 v[104:107], v[160:163], v[196:199], v[104:107]
	v_mfma_f32_16x16x32_bf16 v[92:95], v[144:147], v[204:207], v[92:95]
	v_mfma_f32_16x16x32_bf16 v[88:91], v[160:163], v[204:207], v[88:91]
	v_mfma_f32_16x16x32_bf16 v[76:79], v[144:147], v[212:215], v[76:79]
	v_mfma_f32_16x16x32_bf16 v[72:75], v[160:163], v[212:215], v[72:75]
	v_mfma_f32_16x16x32_bf16 v[124:127], v[156:159], v[192:195], v[124:127]
	v_mfma_f32_16x16x32_bf16 v[120:123], v[164:167], v[192:195], v[120:123]
	v_mfma_f32_16x16x32_bf16 v[108:111], v[156:159], v[200:203], v[108:111]
	v_mfma_f32_16x16x32_bf16 v[104:107], v[164:167], v[200:203], v[104:107]
	v_mfma_f32_16x16x32_bf16 v[92:95], v[156:159], v[208:211], v[92:95]
	v_mfma_f32_16x16x32_bf16 v[88:91], v[164:167], v[208:211], v[88:91]
	v_mfma_f32_16x16x32_bf16 v[76:79], v[156:159], v[216:219], v[76:79]
	v_mfma_f32_16x16x32_bf16 v[72:75], v[164:167], v[216:219], v[72:75]
	v_mfma_f32_16x16x32_bf16 v[116:119], v[168:171], v[188:191], v[116:119]
	v_mfma_f32_16x16x32_bf16 v[112:115], v[176:179], v[188:191], v[112:115]
	v_mfma_f32_16x16x32_bf16 v[100:103], v[168:171], v[196:199], v[100:103]
	v_mfma_f32_16x16x32_bf16 v[96:99], v[176:179], v[196:199], v[96:99]
	v_mfma_f32_16x16x32_bf16 v[84:87], v[168:171], v[204:207], v[84:87]
	v_mfma_f32_16x16x32_bf16 v[80:83], v[176:179], v[204:207], v[80:83]
	v_mfma_f32_16x16x32_bf16 v[68:71], v[168:171], v[212:215], v[68:71]
	v_mfma_f32_16x16x32_bf16 v[64:67], v[176:179], v[212:215], v[64:67]
	v_mfma_f32_16x16x32_bf16 v[116:119], v[172:175], v[192:195], v[116:119]
	v_mfma_f32_16x16x32_bf16 v[112:115], v[184:187], v[192:195], v[112:115]
	v_mfma_f32_16x16x32_bf16 v[100:103], v[172:175], v[200:203], v[100:103]
	v_mfma_f32_16x16x32_bf16 v[96:99], v[184:187], v[200:203], v[96:99]
	v_mfma_f32_16x16x32_bf16 v[84:87], v[172:175], v[208:211], v[84:87]
	v_mfma_f32_16x16x32_bf16 v[80:83], v[184:187], v[208:211], v[80:83]
	v_mfma_f32_16x16x32_bf16 v[68:71], v[172:175], v[216:219], v[68:71]
	v_mfma_f32_16x16x32_bf16 v[64:67], v[184:187], v[216:219], v[64:67]
	s_barrier
	s_add_i32 s18, s37, s28
	v_lshl_add_u64 v[220:221], s[22:23], 0, v[130:131]
	s_mov_b32 m0, s18
	ds_read_b128 v[188:191], v153 offset:16384
	ds_read_b128 v[192:195], v153 offset:17408
	ds_read_b128 v[196:199], v153 offset:18432
	ds_read_b128 v[200:203], v153 offset:19456
	ds_read_b128 v[204:207], v153 offset:20480
	ds_read_b128 v[208:211], v153 offset:21504
	ds_read_b128 v[212:215], v153 offset:22528
	ds_read_b128 v[216:219], v153 offset:23552
	global_load_lds_dwordx4 v[220:221], off
	s_add_i32 m0, s18, 0x2000
	s_add_u32 s18, s22, 0xb0000
	v_lshl_add_u64 v[222:223], s[22:23], 0, v[134:135]
	s_addc_u32 s19, s23, 0
	s_add_i32 s50, s38, s28
	global_load_lds_dwordx4 v[222:223], off
	v_lshl_add_u64 v[224:225], s[18:19], 0, v[130:131]
	s_mov_b32 m0, s50
	global_load_lds_dwordx4 v[224:225], off
	v_lshl_add_u64 v[224:225], s[18:19], 0, v[134:135]
	s_add_i32 m0, s50, 0x2000
	s_nop 0
	global_load_lds_dwordx4 v[224:225], off
	s_waitcnt vmcnt(6)
	s_waitcnt lgkmcnt(0)
	s_barrier
	s_waitcnt lgkmcnt(0)
	v_mfma_f32_16x16x32_bf16 v[60:63], v[144:147], v[188:191], v[60:63]
	v_mfma_f32_16x16x32_bf16 v[56:59], v[160:163], v[188:191], v[56:59]
	v_mfma_f32_16x16x32_bf16 v[44:47], v[144:147], v[196:199], v[44:47]
	v_mfma_f32_16x16x32_bf16 v[40:43], v[160:163], v[196:199], v[40:43]
	v_mfma_f32_16x16x32_bf16 v[28:31], v[144:147], v[204:207], v[28:31]
	v_mfma_f32_16x16x32_bf16 v[24:27], v[160:163], v[204:207], v[24:27]
	v_mfma_f32_16x16x32_bf16 v[12:15], v[144:147], v[212:215], v[12:15]
	v_mfma_f32_16x16x32_bf16 v[8:11], v[160:163], v[212:215], v[8:11]
	v_mfma_f32_16x16x32_bf16 v[60:63], v[156:159], v[192:195], v[60:63]
	v_mfma_f32_16x16x32_bf16 v[56:59], v[164:167], v[192:195], v[56:59]
	v_mfma_f32_16x16x32_bf16 v[44:47], v[156:159], v[200:203], v[44:47]
	v_mfma_f32_16x16x32_bf16 v[40:43], v[164:167], v[200:203], v[40:43]
	v_mfma_f32_16x16x32_bf16 v[28:31], v[156:159], v[208:211], v[28:31]
	v_mfma_f32_16x16x32_bf16 v[24:27], v[164:167], v[208:211], v[24:27]
	v_mfma_f32_16x16x32_bf16 v[12:15], v[156:159], v[216:219], v[12:15]
	v_mfma_f32_16x16x32_bf16 v[8:11], v[164:167], v[216:219], v[8:11]
	v_mfma_f32_16x16x32_bf16 v[52:55], v[168:171], v[188:191], v[52:55]
	v_mfma_f32_16x16x32_bf16 v[48:51], v[176:179], v[188:191], v[48:51]
	v_mfma_f32_16x16x32_bf16 v[36:39], v[168:171], v[196:199], v[36:39]
	v_mfma_f32_16x16x32_bf16 v[32:35], v[176:179], v[196:199], v[32:35]
	v_mfma_f32_16x16x32_bf16 v[20:23], v[168:171], v[204:207], v[20:23]
	v_mfma_f32_16x16x32_bf16 v[16:19], v[176:179], v[204:207], v[16:19]
	v_mfma_f32_16x16x32_bf16 v[4:7], v[168:171], v[212:215], v[4:7]
	v_mfma_f32_16x16x32_bf16 v[0:3], v[176:179], v[212:215], v[0:3]
	v_mfma_f32_16x16x32_bf16 v[52:55], v[172:175], v[192:195], v[52:55]
	v_mfma_f32_16x16x32_bf16 v[48:51], v[184:187], v[192:195], v[48:51]
	v_mfma_f32_16x16x32_bf16 v[36:39], v[172:175], v[200:203], v[36:39]
	v_mfma_f32_16x16x32_bf16 v[32:35], v[184:187], v[200:203], v[32:35]
	v_mfma_f32_16x16x32_bf16 v[20:23], v[172:175], v[208:211], v[20:23]
	v_mfma_f32_16x16x32_bf16 v[16:19], v[184:187], v[208:211], v[16:19]
	v_mfma_f32_16x16x32_bf16 v[4:7], v[172:175], v[216:219], v[4:7]
	v_mfma_f32_16x16x32_bf16 v[0:3], v[184:187], v[216:219], v[0:3]
	s_barrier
	s_add_i32 s50, 0, 0x18000
	v_add_u32_e32 v155, s50, v149
	s_add_i32 s51, 0, 0x1c000
	ds_read_b128 v[144:147], v155
	ds_read_b128 v[156:159], v155 offset:1024
	ds_read_b128 v[160:163], v155 offset:2048
	ds_read_b128 v[164:167], v155 offset:3072
	v_add_u32_e32 v155, s51, v149
	ds_read_b128 v[168:171], v155
	ds_read_b128 v[172:175], v155 offset:1024
	ds_read_b128 v[176:179], v155 offset:2048
	ds_read_b128 v[184:187], v155 offset:3072
	s_add_u32 s18, s24, 0xb0000
	s_addc_u32 s19, s25, 0
	v_lshl_add_u64 v[224:225], s[24:25], 0, v[128:129]
	s_mov_b32 m0, s29
	v_lshl_add_u64 v[226:227], s[24:25], 0, v[132:133]
	global_load_lds_dwordx4 v[224:225], off
	s_mov_b32 m0, s30
	s_nop 0
	global_load_lds_dwordx4 v[226:227], off
	s_mov_b32 m0, s31
	v_lshl_add_u64 v[228:229], s[18:19], 0, v[128:129]
	ds_read_b128 v[188:191], v153 offset:32768
	ds_read_b128 v[192:195], v153 offset:33792
	ds_read_b128 v[196:199], v153 offset:34816
	ds_read_b128 v[200:203], v153 offset:35840
	ds_read_b128 v[204:207], v153 offset:36864
	ds_read_b128 v[208:211], v153 offset:37888
	ds_read_b128 v[212:215], v153 offset:38912
	ds_read_b128 v[216:219], v153 offset:39936
	global_load_lds_dwordx4 v[228:229], off
	v_lshl_add_u64 v[228:229], s[18:19], 0, v[132:133]
	s_mov_b32 m0, s33
	s_nop 0
	global_load_lds_dwordx4 v[228:229], off
	s_waitcnt vmcnt(8)
	s_waitcnt lgkmcnt(0)
	s_barrier
	s_waitcnt lgkmcnt(0)
	v_mfma_f32_16x16x32_bf16 v[124:127], v[144:147], v[188:191], v[124:127]
	v_mfma_f32_16x16x32_bf16 v[120:123], v[160:163], v[188:191], v[120:123]
	v_mfma_f32_16x16x32_bf16 v[108:111], v[144:147], v[196:199], v[108:111]
	v_mfma_f32_16x16x32_bf16 v[104:107], v[160:163], v[196:199], v[104:107]
	v_mfma_f32_16x16x32_bf16 v[92:95], v[144:147], v[204:207], v[92:95]
	v_mfma_f32_16x16x32_bf16 v[88:91], v[160:163], v[204:207], v[88:91]
	v_mfma_f32_16x16x32_bf16 v[76:79], v[144:147], v[212:215], v[76:79]
	v_mfma_f32_16x16x32_bf16 v[72:75], v[160:163], v[212:215], v[72:75]
	v_mfma_f32_16x16x32_bf16 v[124:127], v[156:159], v[192:195], v[124:127]
	v_mfma_f32_16x16x32_bf16 v[120:123], v[164:167], v[192:195], v[120:123]
	v_mfma_f32_16x16x32_bf16 v[108:111], v[156:159], v[200:203], v[108:111]
	v_mfma_f32_16x16x32_bf16 v[104:107], v[164:167], v[200:203], v[104:107]
	v_mfma_f32_16x16x32_bf16 v[92:95], v[156:159], v[208:211], v[92:95]
	v_mfma_f32_16x16x32_bf16 v[88:91], v[164:167], v[208:211], v[88:91]
	v_mfma_f32_16x16x32_bf16 v[76:79], v[156:159], v[216:219], v[76:79]
	v_mfma_f32_16x16x32_bf16 v[72:75], v[164:167], v[216:219], v[72:75]
	v_mfma_f32_16x16x32_bf16 v[116:119], v[168:171], v[188:191], v[116:119]
	v_mfma_f32_16x16x32_bf16 v[112:115], v[176:179], v[188:191], v[112:115]
	v_mfma_f32_16x16x32_bf16 v[100:103], v[168:171], v[196:199], v[100:103]
	v_mfma_f32_16x16x32_bf16 v[96:99], v[176:179], v[196:199], v[96:99]
	v_mfma_f32_16x16x32_bf16 v[84:87], v[168:171], v[204:207], v[84:87]
	v_mfma_f32_16x16x32_bf16 v[80:83], v[176:179], v[204:207], v[80:83]
	v_mfma_f32_16x16x32_bf16 v[68:71], v[168:171], v[212:215], v[68:71]
	v_mfma_f32_16x16x32_bf16 v[64:67], v[176:179], v[212:215], v[64:67]
	v_mfma_f32_16x16x32_bf16 v[116:119], v[172:175], v[192:195], v[116:119]
	v_mfma_f32_16x16x32_bf16 v[112:115], v[184:187], v[192:195], v[112:115]
	v_mfma_f32_16x16x32_bf16 v[100:103], v[172:175], v[200:203], v[100:103]
	v_mfma_f32_16x16x32_bf16 v[96:99], v[184:187], v[200:203], v[96:99]
	v_mfma_f32_16x16x32_bf16 v[84:87], v[172:175], v[208:211], v[84:87]
	v_mfma_f32_16x16x32_bf16 v[80:83], v[184:187], v[208:211], v[80:83]
	v_mfma_f32_16x16x32_bf16 v[68:71], v[172:175], v[216:219], v[68:71]
	v_mfma_f32_16x16x32_bf16 v[64:67], v[184:187], v[216:219], v[64:67]
	s_barrier
	s_add_i32 s18, s50, s28
	v_lshl_add_u64 v[220:221], v[220:221], 0, s[12:13]
	s_mov_b32 m0, s18
	ds_read_b128 v[188:191], v153 offset:49152
	ds_read_b128 v[192:195], v153 offset:50176
	ds_read_b128 v[196:199], v153 offset:51200
	ds_read_b128 v[200:203], v153 offset:52224
	ds_read_b128 v[204:207], v153 offset:53248
	ds_read_b128 v[208:211], v153 offset:54272
	ds_read_b128 v[212:215], v153 offset:55296
	ds_read_b128 v[216:219], v153 offset:56320
	global_load_lds_dwordx4 v[220:221], off
	s_add_i32 m0, s18, 0x2000
	s_add_u32 s18, s22, 0xb0080
	v_lshl_add_u64 v[220:221], v[222:223], 0, s[12:13]
	s_addc_u32 s19, s23, 0
	s_add_i32 s22, s51, s28
	global_load_lds_dwordx4 v[220:221], off
	v_lshl_add_u64 v[220:221], s[18:19], 0, v[130:131]
	s_mov_b32 m0, s22
	s_nop 0
	global_load_lds_dwordx4 v[220:221], off
	v_lshl_add_u64 v[220:221], s[18:19], 0, v[134:135]
	s_add_i32 m0, s22, 0x2000
	s_nop 0
	global_load_lds_dwordx4 v[220:221], off
	s_waitcnt vmcnt(6)
	s_waitcnt lgkmcnt(0)
	s_barrier
	s_waitcnt lgkmcnt(0)
	v_mfma_f32_16x16x32_bf16 v[60:63], v[144:147], v[188:191], v[60:63]
	v_mfma_f32_16x16x32_bf16 v[56:59], v[160:163], v[188:191], v[56:59]
	v_mfma_f32_16x16x32_bf16 v[44:47], v[144:147], v[196:199], v[44:47]
	v_mfma_f32_16x16x32_bf16 v[40:43], v[160:163], v[196:199], v[40:43]
	v_mfma_f32_16x16x32_bf16 v[28:31], v[144:147], v[204:207], v[28:31]
	v_mfma_f32_16x16x32_bf16 v[24:27], v[160:163], v[204:207], v[24:27]
	v_mfma_f32_16x16x32_bf16 v[12:15], v[144:147], v[212:215], v[12:15]
	v_mfma_f32_16x16x32_bf16 v[8:11], v[160:163], v[212:215], v[8:11]
	v_mfma_f32_16x16x32_bf16 v[60:63], v[156:159], v[192:195], v[60:63]
	v_mfma_f32_16x16x32_bf16 v[56:59], v[164:167], v[192:195], v[56:59]
	v_mfma_f32_16x16x32_bf16 v[44:47], v[156:159], v[200:203], v[44:47]
	v_mfma_f32_16x16x32_bf16 v[40:43], v[164:167], v[200:203], v[40:43]
	v_mfma_f32_16x16x32_bf16 v[28:31], v[156:159], v[208:211], v[28:31]
	v_mfma_f32_16x16x32_bf16 v[24:27], v[164:167], v[208:211], v[24:27]
	v_mfma_f32_16x16x32_bf16 v[12:15], v[156:159], v[216:219], v[12:15]
	v_mfma_f32_16x16x32_bf16 v[8:11], v[164:167], v[216:219], v[8:11]
	v_mfma_f32_16x16x32_bf16 v[52:55], v[168:171], v[188:191], v[52:55]
	v_mfma_f32_16x16x32_bf16 v[48:51], v[176:179], v[188:191], v[48:51]
	v_mfma_f32_16x16x32_bf16 v[36:39], v[168:171], v[196:199], v[36:39]
	v_mfma_f32_16x16x32_bf16 v[32:35], v[176:179], v[196:199], v[32:35]
	v_mfma_f32_16x16x32_bf16 v[20:23], v[168:171], v[204:207], v[20:23]
	v_mfma_f32_16x16x32_bf16 v[16:19], v[176:179], v[204:207], v[16:19]
	v_mfma_f32_16x16x32_bf16 v[4:7], v[168:171], v[212:215], v[4:7]
	v_mfma_f32_16x16x32_bf16 v[0:3], v[176:179], v[212:215], v[0:3]
	v_mfma_f32_16x16x32_bf16 v[52:55], v[172:175], v[192:195], v[52:55]
	v_mfma_f32_16x16x32_bf16 v[48:51], v[184:187], v[192:195], v[48:51]
	v_mfma_f32_16x16x32_bf16 v[36:39], v[172:175], v[200:203], v[36:39]
	v_mfma_f32_16x16x32_bf16 v[32:35], v[184:187], v[200:203], v[32:35]
	v_mfma_f32_16x16x32_bf16 v[20:23], v[172:175], v[208:211], v[20:23]
	v_mfma_f32_16x16x32_bf16 v[16:19], v[184:187], v[208:211], v[16:19]
	v_mfma_f32_16x16x32_bf16 v[4:7], v[172:175], v[216:219], v[4:7]
	v_mfma_f32_16x16x32_bf16 v[0:3], v[184:187], v[216:219], v[0:3]
	s_barrier
	v_lshl_add_u64 v[220:221], v[224:225], 0, s[12:13]
	s_mov_b32 m0, s35
	s_nop 0
	global_load_lds_dwordx4 v[220:221], off
	v_lshl_add_u64 v[220:221], v[226:227], 0, s[12:13]
	s_mov_b32 m0, s36
	s_nop 0
	global_load_lds_dwordx4 v[220:221], off
	s_add_i32 s47, s47, 2
	s_add_u32 s43, s43, 0x100
	s_addc_u32 s46, s46, 0
	s_cmp_gt_u32 s47, 41
	s_mov_b64 s[18:19], s[20:21]
	s_cbranch_scc0 .LBB0_787
	s_and_b64 vcc, exec, s[14:15]
	s_cbranch_vccz .LBB0_790
	s_barrier

.LBB0_877:
	ds_read_b128 v[144:147], v173
	ds_read_b128 v[148:151], v173 offset:1024
	ds_read_b128 v[152:155], v173 offset:2048
	ds_read_b128 v[156:159], v173 offset:3072
	ds_read_b128 v[184:187], v174
	ds_read_b128 v[188:191], v174 offset:1024
	ds_read_b128 v[192:195], v174 offset:2048
	ds_read_b128 v[196:199], v174 offset:3072
	s_add_u32 s30, s28, 0xfffc0080
	s_addc_u32 s31, s29, -1
	s_cmp_eq_u32 s56, 12
	s_cselect_b32 s35, s11, s31
	s_cselect_b32 s34, s23, s30
	s_cselect_b32 s31, s21, s55
	s_cselect_b32 s30, s53, s54
	v_lshl_add_u64 v[160:161], s[28:29], 0, v[136:137]
	s_add_i32 m0, s38, 0xc000
	ds_read_b128 v[200:203], v175
	ds_read_b128 v[204:207], v175 offset:1024
	ds_read_b128 v[208:211], v175 offset:2048
	ds_read_b128 v[212:215], v175 offset:3072
	ds_read_b128 v[216:219], v175 offset:4096
	ds_read_b128 v[220:223], v175 offset:5120
	ds_read_b128 v[224:227], v175 offset:6144
	ds_read_b128 v[228:231], v175 offset:7168
	global_load_lds_dwordx4 v[160:161], off
	v_lshl_add_u64 v[160:161], s[28:29], 0, v[138:139]
	s_add_i32 m0, s38, 0xe000
	s_nop 0
	global_load_lds_dwordx4 v[160:161], off
	s_waitcnt vmcnt(8)
	s_waitcnt lgkmcnt(0)
	s_barrier
	s_waitcnt lgkmcnt(0)
	v_mfma_f32_16x16x32_bf16 v[124:127], v[144:147], v[200:203], v[124:127]
	v_mfma_f32_16x16x32_bf16 v[120:123], v[152:155], v[200:203], v[120:123]
	v_mfma_f32_16x16x32_bf16 v[108:111], v[144:147], v[208:211], v[108:111]
	v_mfma_f32_16x16x32_bf16 v[104:107], v[152:155], v[208:211], v[104:107]
	v_mfma_f32_16x16x32_bf16 v[92:95], v[144:147], v[216:219], v[92:95]
	v_mfma_f32_16x16x32_bf16 v[88:91], v[152:155], v[216:219], v[88:91]
	v_mfma_f32_16x16x32_bf16 v[76:79], v[144:147], v[224:227], v[76:79]
	v_mfma_f32_16x16x32_bf16 v[72:75], v[152:155], v[224:227], v[72:75]
	v_mfma_f32_16x16x32_bf16 v[124:127], v[148:151], v[204:207], v[124:127]
	v_mfma_f32_16x16x32_bf16 v[120:123], v[156:159], v[204:207], v[120:123]
	v_mfma_f32_16x16x32_bf16 v[108:111], v[148:151], v[212:215], v[108:111]
	v_mfma_f32_16x16x32_bf16 v[104:107], v[156:159], v[212:215], v[104:107]
	v_mfma_f32_16x16x32_bf16 v[92:95], v[148:151], v[220:223], v[92:95]
	v_mfma_f32_16x16x32_bf16 v[88:91], v[156:159], v[220:223], v[88:91]
	v_mfma_f32_16x16x32_bf16 v[76:79], v[148:151], v[228:231], v[76:79]
	v_mfma_f32_16x16x32_bf16 v[72:75], v[156:159], v[228:231], v[72:75]
	v_mfma_f32_16x16x32_bf16 v[116:119], v[184:187], v[200:203], v[116:119]
	v_mfma_f32_16x16x32_bf16 v[112:115], v[192:195], v[200:203], v[112:115]
	v_mfma_f32_16x16x32_bf16 v[100:103], v[184:187], v[208:211], v[100:103]
	v_mfma_f32_16x16x32_bf16 v[96:99], v[192:195], v[208:211], v[96:99]
	v_mfma_f32_16x16x32_bf16 v[84:87], v[184:187], v[216:219], v[84:87]
	v_mfma_f32_16x16x32_bf16 v[80:83], v[192:195], v[216:219], v[80:83]
	v_mfma_f32_16x16x32_bf16 v[68:71], v[184:187], v[224:227], v[68:71]
	v_mfma_f32_16x16x32_bf16 v[64:67], v[192:195], v[224:227], v[64:67]
	v_mfma_f32_16x16x32_bf16 v[116:119], v[188:191], v[204:207], v[116:119]
	v_mfma_f32_16x16x32_bf16 v[112:115], v[196:199], v[204:207], v[112:115]
	v_mfma_f32_16x16x32_bf16 v[100:103], v[188:191], v[212:215], v[100:103]
	v_mfma_f32_16x16x32_bf16 v[96:99], v[196:199], v[212:215], v[96:99]
	v_mfma_f32_16x16x32_bf16 v[84:87], v[188:191], v[220:223], v[84:87]
	v_mfma_f32_16x16x32_bf16 v[80:83], v[196:199], v[220:223], v[80:83]
	v_mfma_f32_16x16x32_bf16 v[68:71], v[188:191], v[228:231], v[68:71]
	v_mfma_f32_16x16x32_bf16 v[64:67], v[196:199], v[228:231], v[64:67]
	s_barrier
	s_add_i32 s57, s47, s37
	v_lshl_add_u64 v[160:161], s[30:31], 0, v[130:131]
	s_mov_b32 m0, s57
	ds_read_b128 v[200:203], v175 offset:16384
	ds_read_b128 v[204:207], v175 offset:17408
	ds_read_b128 v[208:211], v175 offset:18432
	ds_read_b128 v[212:215], v175 offset:19456
	ds_read_b128 v[216:219], v175 offset:20480
	ds_read_b128 v[220:223], v175 offset:21504
	ds_read_b128 v[224:227], v175 offset:22528
	ds_read_b128 v[228:231], v175 offset:23552
	global_load_lds_dwordx4 v[160:161], off
	s_add_i32 m0, s57, 0x2000
	s_add_u32 s58, s30, 0x40000
	v_lshl_add_u64 v[178:179], s[30:31], 0, v[134:135]
	s_addc_u32 s59, s31, 0
	s_add_i32 s57, s50, s37
	global_load_lds_dwordx4 v[178:179], off
	v_lshl_add_u64 v[232:233], s[58:59], 0, v[130:131]
	s_mov_b32 m0, s57
	global_load_lds_dwordx4 v[232:233], off
	v_lshl_add_u64 v[232:233], s[58:59], 0, v[134:135]
	s_add_i32 m0, s57, 0x2000
	s_nop 0
	global_load_lds_dwordx4 v[232:233], off
	s_waitcnt vmcnt(6)
	s_waitcnt lgkmcnt(0)
	s_barrier
	s_waitcnt lgkmcnt(0)
	v_mfma_f32_16x16x32_bf16 v[60:63], v[144:147], v[200:203], v[60:63]
	v_mfma_f32_16x16x32_bf16 v[56:59], v[152:155], v[200:203], v[56:59]
	v_mfma_f32_16x16x32_bf16 v[44:47], v[144:147], v[208:211], v[44:47]
	v_mfma_f32_16x16x32_bf16 v[40:43], v[152:155], v[208:211], v[40:43]
	v_mfma_f32_16x16x32_bf16 v[28:31], v[144:147], v[216:219], v[28:31]
	v_mfma_f32_16x16x32_bf16 v[24:27], v[152:155], v[216:219], v[24:27]
	v_mfma_f32_16x16x32_bf16 v[12:15], v[144:147], v[224:227], v[12:15]
	v_mfma_f32_16x16x32_bf16 v[8:11], v[152:155], v[224:227], v[8:11]
	v_mfma_f32_16x16x32_bf16 v[60:63], v[148:151], v[204:207], v[60:63]
	v_mfma_f32_16x16x32_bf16 v[56:59], v[156:159], v[204:207], v[56:59]
	v_mfma_f32_16x16x32_bf16 v[44:47], v[148:151], v[212:215], v[44:47]
	v_mfma_f32_16x16x32_bf16 v[40:43], v[156:159], v[212:215], v[40:43]
	v_mfma_f32_16x16x32_bf16 v[28:31], v[148:151], v[220:223], v[28:31]
	v_mfma_f32_16x16x32_bf16 v[24:27], v[156:159], v[220:223], v[24:27]
	v_mfma_f32_16x16x32_bf16 v[12:15], v[148:151], v[228:231], v[12:15]
	v_mfma_f32_16x16x32_bf16 v[8:11], v[156:159], v[228:231], v[8:11]
	v_mfma_f32_16x16x32_bf16 v[52:55], v[184:187], v[200:203], v[52:55]
	v_mfma_f32_16x16x32_bf16 v[48:51], v[192:195], v[200:203], v[48:51]
	v_mfma_f32_16x16x32_bf16 v[36:39], v[184:187], v[208:211], v[36:39]
	v_mfma_f32_16x16x32_bf16 v[32:35], v[192:195], v[208:211], v[32:35]
	v_mfma_f32_16x16x32_bf16 v[20:23], v[184:187], v[216:219], v[20:23]
	v_mfma_f32_16x16x32_bf16 v[16:19], v[192:195], v[216:219], v[16:19]
	v_mfma_f32_16x16x32_bf16 v[4:7], v[184:187], v[224:227], v[4:7]
	v_mfma_f32_16x16x32_bf16 v[0:3], v[192:195], v[224:227], v[0:3]
	v_mfma_f32_16x16x32_bf16 v[52:55], v[188:191], v[204:207], v[52:55]
	v_mfma_f32_16x16x32_bf16 v[48:51], v[196:199], v[204:207], v[48:51]
	v_mfma_f32_16x16x32_bf16 v[36:39], v[188:191], v[212:215], v[36:39]
	v_mfma_f32_16x16x32_bf16 v[32:35], v[196:199], v[212:215], v[32:35]
	v_mfma_f32_16x16x32_bf16 v[20:23], v[188:191], v[220:223], v[20:23]
	v_mfma_f32_16x16x32_bf16 v[16:19], v[196:199], v[220:223], v[16:19]
	v_mfma_f32_16x16x32_bf16 v[4:7], v[188:191], v[228:231], v[4:7]
	v_mfma_f32_16x16x32_bf16 v[0:3], v[196:199], v[228:231], v[0:3]
	s_barrier
	s_add_i32 s57, 0, 0x18000
	s_add_i32 s58, 0, 0x1c000
	v_add_u32_e32 v156, s57, v163
	v_add_u32_e32 v177, s58, v163
	ds_read_b128 v[144:147], v156
	ds_read_b128 v[148:151], v156 offset:1024
	ds_read_b128 v[152:155], v156 offset:2048
	ds_read_b128 v[156:159], v156 offset:3072
	ds_read_b128 v[184:187], v177
	ds_read_b128 v[188:191], v177 offset:1024
	ds_read_b128 v[192:195], v177 offset:2048
	ds_read_b128 v[196:199], v177 offset:3072
	v_lshl_add_u64 v[232:233], s[34:35], 0, v[128:129]
	s_mov_b32 m0, s38
	v_lshl_add_u64 v[234:235], s[34:35], 0, v[132:133]
	global_load_lds_dwordx4 v[232:233], off
	s_mov_b32 m0, s39
	s_nop 0
	global_load_lds_dwordx4 v[234:235], off
	s_add_u32 s34, s34, 0x40000
	s_addc_u32 s35, s35, 0
	s_mov_b32 m0, s40
	v_lshl_add_u64 v[236:237], s[34:35], 0, v[128:129]
	ds_read_b128 v[200:203], v175 offset:32768
	ds_read_b128 v[204:207], v175 offset:33792
	ds_read_b128 v[208:211], v175 offset:34816
	ds_read_b128 v[212:215], v175 offset:35840
	ds_read_b128 v[216:219], v175 offset:36864
	ds_read_b128 v[220:223], v175 offset:37888
	ds_read_b128 v[224:227], v175 offset:38912
	ds_read_b128 v[228:231], v175 offset:39936
	global_load_lds_dwordx4 v[236:237], off
	v_lshl_add_u64 v[236:237], s[34:35], 0, v[132:133]
	s_mov_b32 m0, s41
	s_nop 0
	global_load_lds_dwordx4 v[236:237], off
	s_waitcnt vmcnt(8)
	s_waitcnt lgkmcnt(0)
	s_barrier
	s_waitcnt lgkmcnt(0)
	v_mfma_f32_16x16x32_bf16 v[124:127], v[144:147], v[200:203], v[124:127]
	v_mfma_f32_16x16x32_bf16 v[120:123], v[152:155], v[200:203], v[120:123]
	v_mfma_f32_16x16x32_bf16 v[108:111], v[144:147], v[208:211], v[108:111]
	v_mfma_f32_16x16x32_bf16 v[104:107], v[152:155], v[208:211], v[104:107]
	v_mfma_f32_16x16x32_bf16 v[92:95], v[144:147], v[216:219], v[92:95]
	v_mfma_f32_16x16x32_bf16 v[88:91], v[152:155], v[216:219], v[88:91]
	v_mfma_f32_16x16x32_bf16 v[76:79], v[144:147], v[224:227], v[76:79]
	v_mfma_f32_16x16x32_bf16 v[72:75], v[152:155], v[224:227], v[72:75]
	v_mfma_f32_16x16x32_bf16 v[124:127], v[148:151], v[204:207], v[124:127]
	v_mfma_f32_16x16x32_bf16 v[120:123], v[156:159], v[204:207], v[120:123]
	v_mfma_f32_16x16x32_bf16 v[108:111], v[148:151], v[212:215], v[108:111]
	v_mfma_f32_16x16x32_bf16 v[104:107], v[156:159], v[212:215], v[104:107]
	v_mfma_f32_16x16x32_bf16 v[92:95], v[148:151], v[220:223], v[92:95]
	v_mfma_f32_16x16x32_bf16 v[88:91], v[156:159], v[220:223], v[88:91]
	v_mfma_f32_16x16x32_bf16 v[76:79], v[148:151], v[228:231], v[76:79]
	v_mfma_f32_16x16x32_bf16 v[72:75], v[156:159], v[228:231], v[72:75]
	v_mfma_f32_16x16x32_bf16 v[116:119], v[184:187], v[200:203], v[116:119]
	v_mfma_f32_16x16x32_bf16 v[112:115], v[192:195], v[200:203], v[112:115]
	v_mfma_f32_16x16x32_bf16 v[100:103], v[184:187], v[208:211], v[100:103]
	v_mfma_f32_16x16x32_bf16 v[96:99], v[192:195], v[208:211], v[96:99]
	v_mfma_f32_16x16x32_bf16 v[84:87], v[184:187], v[216:219], v[84:87]
	v_mfma_f32_16x16x32_bf16 v[80:83], v[192:195], v[216:219], v[80:83]
	v_mfma_f32_16x16x32_bf16 v[68:71], v[184:187], v[224:227], v[68:71]
	v_mfma_f32_16x16x32_bf16 v[64:67], v[192:195], v[224:227], v[64:67]
	v_mfma_f32_16x16x32_bf16 v[116:119], v[188:191], v[204:207], v[116:119]
	v_mfma_f32_16x16x32_bf16 v[112:115], v[196:199], v[204:207], v[112:115]
	v_mfma_f32_16x16x32_bf16 v[100:103], v[188:191], v[212:215], v[100:103]
	v_mfma_f32_16x16x32_bf16 v[96:99], v[196:199], v[212:215], v[96:99]
	v_mfma_f32_16x16x32_bf16 v[84:87], v[188:191], v[220:223], v[84:87]
	v_mfma_f32_16x16x32_bf16 v[80:83], v[196:199], v[220:223], v[80:83]
	v_mfma_f32_16x16x32_bf16 v[68:71], v[188:191], v[228:231], v[68:71]
	v_mfma_f32_16x16x32_bf16 v[64:67], v[196:199], v[228:231], v[64:67]
	s_barrier
	s_add_i32 s34, s57, s37
	v_lshl_add_u64 v[160:161], v[160:161], 0, s[14:15]
	s_mov_b32 m0, s34
	ds_read_b128 v[200:203], v175 offset:49152
	ds_read_b128 v[204:207], v175 offset:50176
	ds_read_b128 v[208:211], v175 offset:51200
	ds_read_b128 v[212:215], v175 offset:52224
	ds_read_b128 v[216:219], v175 offset:53248
	ds_read_b128 v[220:223], v175 offset:54272
	ds_read_b128 v[224:227], v175 offset:55296
	ds_read_b128 v[228:231], v175 offset:56320
	global_load_lds_dwordx4 v[160:161], off
	s_add_i32 m0, s34, 0x2000
	s_add_u32 s30, s30, 0x40080
	v_lshl_add_u64 v[160:161], v[178:179], 0, s[14:15]
	s_addc_u32 s31, s31, 0
	s_add_i32 s34, s58, s37
	global_load_lds_dwordx4 v[160:161], off
	v_lshl_add_u64 v[160:161], s[30:31], 0, v[130:131]
	s_mov_b32 m0, s34
	s_nop 0
	global_load_lds_dwordx4 v[160:161], off
	v_lshl_add_u64 v[160:161], s[30:31], 0, v[134:135]
	s_add_i32 m0, s34, 0x2000
	s_nop 0
	global_load_lds_dwordx4 v[160:161], off
	s_waitcnt vmcnt(6)
	s_waitcnt lgkmcnt(0)
	s_barrier
	s_waitcnt lgkmcnt(0)
	v_mfma_f32_16x16x32_bf16 v[60:63], v[144:147], v[200:203], v[60:63]
	v_mfma_f32_16x16x32_bf16 v[56:59], v[152:155], v[200:203], v[56:59]
	v_mfma_f32_16x16x32_bf16 v[44:47], v[144:147], v[208:211], v[44:47]
	v_mfma_f32_16x16x32_bf16 v[40:43], v[152:155], v[208:211], v[40:43]
	v_mfma_f32_16x16x32_bf16 v[28:31], v[144:147], v[216:219], v[28:31]
	v_mfma_f32_16x16x32_bf16 v[24:27], v[152:155], v[216:219], v[24:27]
	v_mfma_f32_16x16x32_bf16 v[12:15], v[144:147], v[224:227], v[12:15]
	v_mfma_f32_16x16x32_bf16 v[8:11], v[152:155], v[224:227], v[8:11]
	v_mfma_f32_16x16x32_bf16 v[60:63], v[148:151], v[204:207], v[60:63]
	v_mfma_f32_16x16x32_bf16 v[56:59], v[156:159], v[204:207], v[56:59]
	v_mfma_f32_16x16x32_bf16 v[44:47], v[148:151], v[212:215], v[44:47]
	v_mfma_f32_16x16x32_bf16 v[40:43], v[156:159], v[212:215], v[40:43]
	v_mfma_f32_16x16x32_bf16 v[28:31], v[148:151], v[220:223], v[28:31]
	v_mfma_f32_16x16x32_bf16 v[24:27], v[156:159], v[220:223], v[24:27]
	v_mfma_f32_16x16x32_bf16 v[12:15], v[148:151], v[228:231], v[12:15]
	v_mfma_f32_16x16x32_bf16 v[8:11], v[156:159], v[228:231], v[8:11]
	v_mfma_f32_16x16x32_bf16 v[52:55], v[184:187], v[200:203], v[52:55]
	v_mfma_f32_16x16x32_bf16 v[48:51], v[192:195], v[200:203], v[48:51]
	v_mfma_f32_16x16x32_bf16 v[36:39], v[184:187], v[208:211], v[36:39]
	v_mfma_f32_16x16x32_bf16 v[32:35], v[192:195], v[208:211], v[32:35]
	v_mfma_f32_16x16x32_bf16 v[20:23], v[184:187], v[216:219], v[20:23]
	v_mfma_f32_16x16x32_bf16 v[16:19], v[192:195], v[216:219], v[16:19]
	v_mfma_f32_16x16x32_bf16 v[4:7], v[184:187], v[224:227], v[4:7]
	v_mfma_f32_16x16x32_bf16 v[0:3], v[192:195], v[224:227], v[0:3]
	v_mfma_f32_16x16x32_bf16 v[52:55], v[188:191], v[204:207], v[52:55]
	v_mfma_f32_16x16x32_bf16 v[48:51], v[196:199], v[204:207], v[48:51]
	v_mfma_f32_16x16x32_bf16 v[36:39], v[188:191], v[212:215], v[36:39]
	v_mfma_f32_16x16x32_bf16 v[32:35], v[196:199], v[212:215], v[32:35]
	v_mfma_f32_16x16x32_bf16 v[20:23], v[188:191], v[220:223], v[20:23]
	v_mfma_f32_16x16x32_bf16 v[16:19], v[196:199], v[220:223], v[16:19]
	v_mfma_f32_16x16x32_bf16 v[4:7], v[188:191], v[228:231], v[4:7]
	v_mfma_f32_16x16x32_bf16 v[0:3], v[196:199], v[228:231], v[0:3]
	s_barrier
	v_lshl_add_u64 v[160:161], v[232:233], 0, s[14:15]
	s_mov_b32 m0, s42
	s_nop 0
	global_load_lds_dwordx4 v[160:161], off
	v_lshl_add_u64 v[160:161], v[234:235], 0, s[14:15]
	s_mov_b32 m0, s43
	s_nop 0
	global_load_lds_dwordx4 v[160:161], off
	s_add_i32 s56, s56, 2
	s_add_u32 s28, s28, 0x100
	s_addc_u32 s29, s29, 0
	s_add_u32 s54, s54, 0x100
	s_addc_u32 s55, s55, 0
	s_cmp_gt_u32 s56, 13
	s_cbranch_scc0 .LBB0_877
	s_and_b64 vcc, exec, s[16:17]
	s_cbranch_vccz .LBB0_880
	s_barrier

.LBB0_1291:
	ds_read_b128 v[144:147], v151
	ds_read_b128 v[156:159], v151 offset:1024
	ds_read_b128 v[160:163], v151 offset:2048
	ds_read_b128 v[164:167], v151 offset:3072
	ds_read_b128 v[168:171], v152
	ds_read_b128 v[172:175], v152 offset:1024
	ds_read_b128 v[176:179], v152 offset:2048
	ds_read_b128 v[184:187], v152 offset:3072
	s_add_u32 s26, s24, 0xfffc0080
	s_addc_u32 s27, s25, -1
	s_cmp_eq_u32 s47, 12
	s_cselect_b32 s29, s17, s27
	s_cselect_b32 s28, s23, s26
	s_cselect_b32 s27, s15, s46
	s_cselect_b32 s26, s44, s45
	v_lshl_add_u64 v[220:221], s[24:25], 0, v[136:137]
	s_add_i32 m0, s34, 0xc000
	ds_read_b128 v[188:191], v153
	ds_read_b128 v[192:195], v153 offset:1024
	ds_read_b128 v[196:199], v153 offset:2048
	ds_read_b128 v[200:203], v153 offset:3072
	ds_read_b128 v[204:207], v153 offset:4096
	ds_read_b128 v[208:211], v153 offset:5120
	ds_read_b128 v[212:215], v153 offset:6144
	ds_read_b128 v[216:219], v153 offset:7168
	global_load_lds_dwordx4 v[220:221], off
	v_lshl_add_u64 v[220:221], s[24:25], 0, v[138:139]
	s_add_i32 m0, s34, 0xe000
	s_nop 0
	global_load_lds_dwordx4 v[220:221], off
	s_waitcnt vmcnt(8)
	s_waitcnt lgkmcnt(0)
	s_barrier
	s_waitcnt lgkmcnt(0)
	v_mfma_f32_16x16x32_bf16 v[124:127], v[144:147], v[188:191], v[124:127]
	v_mfma_f32_16x16x32_bf16 v[120:123], v[160:163], v[188:191], v[120:123]
	v_mfma_f32_16x16x32_bf16 v[108:111], v[144:147], v[196:199], v[108:111]
	v_mfma_f32_16x16x32_bf16 v[104:107], v[160:163], v[196:199], v[104:107]
	v_mfma_f32_16x16x32_bf16 v[92:95], v[144:147], v[204:207], v[92:95]
	v_mfma_f32_16x16x32_bf16 v[88:91], v[160:163], v[204:207], v[88:91]
	v_mfma_f32_16x16x32_bf16 v[76:79], v[144:147], v[212:215], v[76:79]
	v_mfma_f32_16x16x32_bf16 v[72:75], v[160:163], v[212:215], v[72:75]
	v_mfma_f32_16x16x32_bf16 v[124:127], v[156:159], v[192:195], v[124:127]
	v_mfma_f32_16x16x32_bf16 v[120:123], v[164:167], v[192:195], v[120:123]
	v_mfma_f32_16x16x32_bf16 v[108:111], v[156:159], v[200:203], v[108:111]
	v_mfma_f32_16x16x32_bf16 v[104:107], v[164:167], v[200:203], v[104:107]
	v_mfma_f32_16x16x32_bf16 v[92:95], v[156:159], v[208:211], v[92:95]
	v_mfma_f32_16x16x32_bf16 v[88:91], v[164:167], v[208:211], v[88:91]
	v_mfma_f32_16x16x32_bf16 v[76:79], v[156:159], v[216:219], v[76:79]
	v_mfma_f32_16x16x32_bf16 v[72:75], v[164:167], v[216:219], v[72:75]
	v_mfma_f32_16x16x32_bf16 v[116:119], v[168:171], v[188:191], v[116:119]
	v_mfma_f32_16x16x32_bf16 v[112:115], v[176:179], v[188:191], v[112:115]
	v_mfma_f32_16x16x32_bf16 v[100:103], v[168:171], v[196:199], v[100:103]
	v_mfma_f32_16x16x32_bf16 v[96:99], v[176:179], v[196:199], v[96:99]
	v_mfma_f32_16x16x32_bf16 v[84:87], v[168:171], v[204:207], v[84:87]
	v_mfma_f32_16x16x32_bf16 v[80:83], v[176:179], v[204:207], v[80:83]
	v_mfma_f32_16x16x32_bf16 v[68:71], v[168:171], v[212:215], v[68:71]
	v_mfma_f32_16x16x32_bf16 v[64:67], v[176:179], v[212:215], v[64:67]
	v_mfma_f32_16x16x32_bf16 v[116:119], v[172:175], v[192:195], v[116:119]
	v_mfma_f32_16x16x32_bf16 v[112:115], v[184:187], v[192:195], v[112:115]
	v_mfma_f32_16x16x32_bf16 v[100:103], v[172:175], v[200:203], v[100:103]
	v_mfma_f32_16x16x32_bf16 v[96:99], v[184:187], v[200:203], v[96:99]
	v_mfma_f32_16x16x32_bf16 v[84:87], v[172:175], v[208:211], v[84:87]
	v_mfma_f32_16x16x32_bf16 v[80:83], v[184:187], v[208:211], v[80:83]
	v_mfma_f32_16x16x32_bf16 v[68:71], v[172:175], v[216:219], v[68:71]
	v_mfma_f32_16x16x32_bf16 v[64:67], v[184:187], v[216:219], v[64:67]
	s_barrier
	s_add_i32 s50, s41, s33
	v_lshl_add_u64 v[220:221], s[26:27], 0, v[130:131]
	s_mov_b32 m0, s50
	ds_read_b128 v[188:191], v153 offset:16384
	ds_read_b128 v[192:195], v153 offset:17408
	ds_read_b128 v[196:199], v153 offset:18432
	ds_read_b128 v[200:203], v153 offset:19456
	ds_read_b128 v[204:207], v153 offset:20480
	ds_read_b128 v[208:211], v153 offset:21504
	ds_read_b128 v[212:215], v153 offset:22528
	ds_read_b128 v[216:219], v153 offset:23552
	global_load_lds_dwordx4 v[220:221], off
	s_add_i32 m0, s50, 0x2000
	s_add_u32 s50, s26, 0x40000
	v_lshl_add_u64 v[222:223], s[26:27], 0, v[134:135]
	s_addc_u32 s51, s27, 0
	s_add_i32 s52, s42, s33
	global_load_lds_dwordx4 v[222:223], off
	v_lshl_add_u64 v[224:225], s[50:51], 0, v[130:131]
	s_mov_b32 m0, s52
	global_load_lds_dwordx4 v[224:225], off
	v_lshl_add_u64 v[224:225], s[50:51], 0, v[134:135]
	s_add_i32 m0, s52, 0x2000
	s_nop 0
	global_load_lds_dwordx4 v[224:225], off
	s_waitcnt vmcnt(6)
	s_waitcnt lgkmcnt(0)
	s_barrier
	s_waitcnt lgkmcnt(0)
	v_mfma_f32_16x16x32_bf16 v[60:63], v[144:147], v[188:191], v[60:63]
	v_mfma_f32_16x16x32_bf16 v[56:59], v[160:163], v[188:191], v[56:59]
	v_mfma_f32_16x16x32_bf16 v[44:47], v[144:147], v[196:199], v[44:47]
	v_mfma_f32_16x16x32_bf16 v[40:43], v[160:163], v[196:199], v[40:43]
	v_mfma_f32_16x16x32_bf16 v[28:31], v[144:147], v[204:207], v[28:31]
	v_mfma_f32_16x16x32_bf16 v[24:27], v[160:163], v[204:207], v[24:27]
	v_mfma_f32_16x16x32_bf16 v[12:15], v[144:147], v[212:215], v[12:15]
	v_mfma_f32_16x16x32_bf16 v[8:11], v[160:163], v[212:215], v[8:11]
	v_mfma_f32_16x16x32_bf16 v[60:63], v[156:159], v[192:195], v[60:63]
	v_mfma_f32_16x16x32_bf16 v[56:59], v[164:167], v[192:195], v[56:59]
	v_mfma_f32_16x16x32_bf16 v[44:47], v[156:159], v[200:203], v[44:47]
	v_mfma_f32_16x16x32_bf16 v[40:43], v[164:167], v[200:203], v[40:43]
	v_mfma_f32_16x16x32_bf16 v[28:31], v[156:159], v[208:211], v[28:31]
	v_mfma_f32_16x16x32_bf16 v[24:27], v[164:167], v[208:211], v[24:27]
	v_mfma_f32_16x16x32_bf16 v[12:15], v[156:159], v[216:219], v[12:15]
	v_mfma_f32_16x16x32_bf16 v[8:11], v[164:167], v[216:219], v[8:11]
	v_mfma_f32_16x16x32_bf16 v[52:55], v[168:171], v[188:191], v[52:55]
	v_mfma_f32_16x16x32_bf16 v[48:51], v[176:179], v[188:191], v[48:51]
	v_mfma_f32_16x16x32_bf16 v[36:39], v[168:171], v[196:199], v[36:39]
	v_mfma_f32_16x16x32_bf16 v[32:35], v[176:179], v[196:199], v[32:35]
	v_mfma_f32_16x16x32_bf16 v[20:23], v[168:171], v[204:207], v[20:23]
	v_mfma_f32_16x16x32_bf16 v[16:19], v[176:179], v[204:207], v[16:19]
	v_mfma_f32_16x16x32_bf16 v[4:7], v[168:171], v[212:215], v[4:7]
	v_mfma_f32_16x16x32_bf16 v[0:3], v[176:179], v[212:215], v[0:3]
	v_mfma_f32_16x16x32_bf16 v[52:55], v[172:175], v[192:195], v[52:55]
	v_mfma_f32_16x16x32_bf16 v[48:51], v[184:187], v[192:195], v[48:51]
	v_mfma_f32_16x16x32_bf16 v[36:39], v[172:175], v[200:203], v[36:39]
	v_mfma_f32_16x16x32_bf16 v[32:35], v[184:187], v[200:203], v[32:35]
	v_mfma_f32_16x16x32_bf16 v[20:23], v[172:175], v[208:211], v[20:23]
	v_mfma_f32_16x16x32_bf16 v[16:19], v[184:187], v[208:211], v[16:19]
	v_mfma_f32_16x16x32_bf16 v[4:7], v[172:175], v[216:219], v[4:7]
	v_mfma_f32_16x16x32_bf16 v[0:3], v[184:187], v[216:219], v[0:3]
	s_barrier
	s_add_i32 s50, 0, 0x18000
	v_add_u32_e32 v155, s50, v149
	s_add_i32 s51, 0, 0x1c000
	ds_read_b128 v[144:147], v155
	ds_read_b128 v[156:159], v155 offset:1024
	ds_read_b128 v[160:163], v155 offset:2048
	ds_read_b128 v[164:167], v155 offset:3072
	v_add_u32_e32 v155, s51, v149
	ds_read_b128 v[168:171], v155
	ds_read_b128 v[172:175], v155 offset:1024
	ds_read_b128 v[176:179], v155 offset:2048
	ds_read_b128 v[184:187], v155 offset:3072
	v_lshl_add_u64 v[224:225], s[28:29], 0, v[128:129]
	s_mov_b32 m0, s34
	v_lshl_add_u64 v[226:227], s[28:29], 0, v[132:133]
	global_load_lds_dwordx4 v[224:225], off
	s_mov_b32 m0, s35
	s_nop 0
	global_load_lds_dwordx4 v[226:227], off
	s_add_u32 s28, s28, 0x40000
	s_addc_u32 s29, s29, 0
	s_mov_b32 m0, s36
	v_lshl_add_u64 v[228:229], s[28:29], 0, v[128:129]
	ds_read_b128 v[188:191], v153 offset:32768
	ds_read_b128 v[192:195], v153 offset:33792
	ds_read_b128 v[196:199], v153 offset:34816
	ds_read_b128 v[200:203], v153 offset:35840
	ds_read_b128 v[204:207], v153 offset:36864
	ds_read_b128 v[208:211], v153 offset:37888
	ds_read_b128 v[212:215], v153 offset:38912
	ds_read_b128 v[216:219], v153 offset:39936
	global_load_lds_dwordx4 v[228:229], off
	v_lshl_add_u64 v[228:229], s[28:29], 0, v[132:133]
	s_mov_b32 m0, s37
	s_nop 0
	global_load_lds_dwordx4 v[228:229], off
	s_waitcnt vmcnt(8)
	s_waitcnt lgkmcnt(0)
	s_barrier
	s_waitcnt lgkmcnt(0)
	v_mfma_f32_16x16x32_bf16 v[124:127], v[144:147], v[188:191], v[124:127]
	v_mfma_f32_16x16x32_bf16 v[120:123], v[160:163], v[188:191], v[120:123]
	v_mfma_f32_16x16x32_bf16 v[108:111], v[144:147], v[196:199], v[108:111]
	v_mfma_f32_16x16x32_bf16 v[104:107], v[160:163], v[196:199], v[104:107]
	v_mfma_f32_16x16x32_bf16 v[92:95], v[144:147], v[204:207], v[92:95]
	v_mfma_f32_16x16x32_bf16 v[88:91], v[160:163], v[204:207], v[88:91]
	v_mfma_f32_16x16x32_bf16 v[76:79], v[144:147], v[212:215], v[76:79]
	v_mfma_f32_16x16x32_bf16 v[72:75], v[160:163], v[212:215], v[72:75]
	v_mfma_f32_16x16x32_bf16 v[124:127], v[156:159], v[192:195], v[124:127]
	v_mfma_f32_16x16x32_bf16 v[120:123], v[164:167], v[192:195], v[120:123]
	v_mfma_f32_16x16x32_bf16 v[108:111], v[156:159], v[200:203], v[108:111]
	v_mfma_f32_16x16x32_bf16 v[104:107], v[164:167], v[200:203], v[104:107]
	v_mfma_f32_16x16x32_bf16 v[92:95], v[156:159], v[208:211], v[92:95]
	v_mfma_f32_16x16x32_bf16 v[88:91], v[164:167], v[208:211], v[88:91]
	v_mfma_f32_16x16x32_bf16 v[76:79], v[156:159], v[216:219], v[76:79]
	v_mfma_f32_16x16x32_bf16 v[72:75], v[164:167], v[216:219], v[72:75]
	v_mfma_f32_16x16x32_bf16 v[116:119], v[168:171], v[188:191], v[116:119]
	v_mfma_f32_16x16x32_bf16 v[112:115], v[176:179], v[188:191], v[112:115]
	v_mfma_f32_16x16x32_bf16 v[100:103], v[168:171], v[196:199], v[100:103]
	v_mfma_f32_16x16x32_bf16 v[96:99], v[176:179], v[196:199], v[96:99]
	v_mfma_f32_16x16x32_bf16 v[84:87], v[168:171], v[204:207], v[84:87]
	v_mfma_f32_16x16x32_bf16 v[80:83], v[176:179], v[204:207], v[80:83]
	v_mfma_f32_16x16x32_bf16 v[68:71], v[168:171], v[212:215], v[68:71]
	v_mfma_f32_16x16x32_bf16 v[64:67], v[176:179], v[212:215], v[64:67]
	v_mfma_f32_16x16x32_bf16 v[116:119], v[172:175], v[192:195], v[116:119]
	v_mfma_f32_16x16x32_bf16 v[112:115], v[184:187], v[192:195], v[112:115]
	v_mfma_f32_16x16x32_bf16 v[100:103], v[172:175], v[200:203], v[100:103]
	v_mfma_f32_16x16x32_bf16 v[96:99], v[184:187], v[200:203], v[96:99]
	v_mfma_f32_16x16x32_bf16 v[84:87], v[172:175], v[208:211], v[84:87]
	v_mfma_f32_16x16x32_bf16 v[80:83], v[184:187], v[208:211], v[80:83]
	v_mfma_f32_16x16x32_bf16 v[68:71], v[172:175], v[216:219], v[68:71]
	v_mfma_f32_16x16x32_bf16 v[64:67], v[184:187], v[216:219], v[64:67]
	s_barrier
	s_add_i32 s28, s50, s33
	v_lshl_add_u64 v[220:221], v[220:221], 0, s[10:11]
	s_mov_b32 m0, s28
	ds_read_b128 v[188:191], v153 offset:49152
	ds_read_b128 v[192:195], v153 offset:50176
	ds_read_b128 v[196:199], v153 offset:51200
	ds_read_b128 v[200:203], v153 offset:52224
	ds_read_b128 v[204:207], v153 offset:53248
	ds_read_b128 v[208:211], v153 offset:54272
	ds_read_b128 v[212:215], v153 offset:55296
	ds_read_b128 v[216:219], v153 offset:56320
	global_load_lds_dwordx4 v[220:221], off
	s_add_i32 m0, s28, 0x2000
	s_add_u32 s26, s26, 0x40080
	v_lshl_add_u64 v[220:221], v[222:223], 0, s[10:11]
	s_addc_u32 s27, s27, 0
	s_add_i32 s28, s51, s33
	global_load_lds_dwordx4 v[220:221], off
	v_lshl_add_u64 v[220:221], s[26:27], 0, v[130:131]
	s_mov_b32 m0, s28
	s_nop 0
	global_load_lds_dwordx4 v[220:221], off
	v_lshl_add_u64 v[220:221], s[26:27], 0, v[134:135]
	s_add_i32 m0, s28, 0x2000
	s_nop 0
	global_load_lds_dwordx4 v[220:221], off
	s_waitcnt vmcnt(6)
	s_waitcnt lgkmcnt(0)
	s_barrier
	s_waitcnt lgkmcnt(0)
	v_mfma_f32_16x16x32_bf16 v[60:63], v[144:147], v[188:191], v[60:63]
	v_mfma_f32_16x16x32_bf16 v[56:59], v[160:163], v[188:191], v[56:59]
	v_mfma_f32_16x16x32_bf16 v[44:47], v[144:147], v[196:199], v[44:47]
	v_mfma_f32_16x16x32_bf16 v[40:43], v[160:163], v[196:199], v[40:43]
	v_mfma_f32_16x16x32_bf16 v[28:31], v[144:147], v[204:207], v[28:31]
	v_mfma_f32_16x16x32_bf16 v[24:27], v[160:163], v[204:207], v[24:27]
	v_mfma_f32_16x16x32_bf16 v[12:15], v[144:147], v[212:215], v[12:15]
	v_mfma_f32_16x16x32_bf16 v[8:11], v[160:163], v[212:215], v[8:11]
	v_mfma_f32_16x16x32_bf16 v[60:63], v[156:159], v[192:195], v[60:63]
	v_mfma_f32_16x16x32_bf16 v[56:59], v[164:167], v[192:195], v[56:59]
	v_mfma_f32_16x16x32_bf16 v[44:47], v[156:159], v[200:203], v[44:47]
	v_mfma_f32_16x16x32_bf16 v[40:43], v[164:167], v[200:203], v[40:43]
	v_mfma_f32_16x16x32_bf16 v[28:31], v[156:159], v[208:211], v[28:31]
	v_mfma_f32_16x16x32_bf16 v[24:27], v[164:167], v[208:211], v[24:27]
	v_mfma_f32_16x16x32_bf16 v[12:15], v[156:159], v[216:219], v[12:15]
	v_mfma_f32_16x16x32_bf16 v[8:11], v[164:167], v[216:219], v[8:11]
	v_mfma_f32_16x16x32_bf16 v[52:55], v[168:171], v[188:191], v[52:55]
	v_mfma_f32_16x16x32_bf16 v[48:51], v[176:179], v[188:191], v[48:51]
	v_mfma_f32_16x16x32_bf16 v[36:39], v[168:171], v[196:199], v[36:39]
	v_mfma_f32_16x16x32_bf16 v[32:35], v[176:179], v[196:199], v[32:35]
	v_mfma_f32_16x16x32_bf16 v[20:23], v[168:171], v[204:207], v[20:23]
	v_mfma_f32_16x16x32_bf16 v[16:19], v[176:179], v[204:207], v[16:19]
	v_mfma_f32_16x16x32_bf16 v[4:7], v[168:171], v[212:215], v[4:7]
	v_mfma_f32_16x16x32_bf16 v[0:3], v[176:179], v[212:215], v[0:3]
	v_mfma_f32_16x16x32_bf16 v[52:55], v[172:175], v[192:195], v[52:55]
	v_mfma_f32_16x16x32_bf16 v[48:51], v[184:187], v[192:195], v[48:51]
	v_mfma_f32_16x16x32_bf16 v[36:39], v[172:175], v[200:203], v[36:39]
	v_mfma_f32_16x16x32_bf16 v[32:35], v[184:187], v[200:203], v[32:35]
	v_mfma_f32_16x16x32_bf16 v[20:23], v[172:175], v[208:211], v[20:23]
	v_mfma_f32_16x16x32_bf16 v[16:19], v[184:187], v[208:211], v[16:19]
	v_mfma_f32_16x16x32_bf16 v[4:7], v[172:175], v[216:219], v[4:7]
	v_mfma_f32_16x16x32_bf16 v[0:3], v[184:187], v[216:219], v[0:3]
	s_barrier
	v_lshl_add_u64 v[220:221], v[224:225], 0, s[10:11]
	s_mov_b32 m0, s39
	s_nop 0
	global_load_lds_dwordx4 v[220:221], off
	v_lshl_add_u64 v[220:221], v[226:227], 0, s[10:11]
	s_mov_b32 m0, s40
	s_nop 0
	global_load_lds_dwordx4 v[220:221], off
	s_add_i32 s47, s47, 2
	s_add_u32 s24, s24, 0x100
	s_addc_u32 s25, s25, 0
	s_add_u32 s45, s45, 0x100
	s_addc_u32 s46, s46, 0
	s_cmp_gt_u32 s47, 13
	s_cbranch_scc0 .LBB0_1291
	s_and_b64 vcc, exec, s[12:13]
	s_cbranch_vccz .LBB0_1294
	s_barrier

.LBB0_1379:
	ds_read_b128 v[154:157], v151
	ds_read_b128 v[158:161], v151 offset:1024
	ds_read_b128 v[162:165], v151 offset:2048
	ds_read_b128 v[166:169], v151 offset:3072
	ds_read_b128 v[170:173], v152
	ds_read_b128 v[174:177], v152 offset:1024
	ds_read_b128 v[184:187], v152 offset:2048
	ds_read_b128 v[188:191], v152 offset:3072
	s_add_u32 s22, s20, 0xfffc0080
	s_addc_u32 s23, s21, -1
	s_cmp_eq_u32 s46, 12
	s_cselect_b32 s25, s13, s23
	s_cselect_b32 s24, s42, s22
	s_cselect_b32 s23, s11, s45
	s_cselect_b32 s22, s43, s44
	v_lshl_add_u64 v[178:179], s[20:21], 0, v[136:137]
	s_add_i32 m0, s19, 0xc000
	ds_read_b128 v[192:195], v153
	ds_read_b128 v[196:199], v153 offset:1024
	ds_read_b128 v[200:203], v153 offset:2048
	ds_read_b128 v[204:207], v153 offset:3072
	ds_read_b128 v[208:211], v153 offset:4096
	ds_read_b128 v[212:215], v153 offset:5120
	ds_read_b128 v[216:219], v153 offset:6144
	ds_read_b128 v[220:223], v153 offset:7168
	global_load_lds_dwordx4 v[178:179], off
	v_lshl_add_u64 v[178:179], s[20:21], 0, v[138:139]
	s_add_i32 m0, s19, 0xe000
	s_nop 0
	global_load_lds_dwordx4 v[178:179], off
	s_waitcnt vmcnt(8)
	s_waitcnt lgkmcnt(0)
	s_barrier
	s_waitcnt lgkmcnt(0)
	v_mfma_f32_16x16x32_bf16 v[124:127], v[154:157], v[192:195], v[124:127]
	v_mfma_f32_16x16x32_bf16 v[116:119], v[162:165], v[192:195], v[116:119]
	v_mfma_f32_16x16x32_bf16 v[108:111], v[154:157], v[200:203], v[108:111]
	v_mfma_f32_16x16x32_bf16 v[100:103], v[162:165], v[200:203], v[100:103]
	v_mfma_f32_16x16x32_bf16 v[92:95], v[154:157], v[208:211], v[92:95]
	v_mfma_f32_16x16x32_bf16 v[84:87], v[162:165], v[208:211], v[84:87]
	v_mfma_f32_16x16x32_bf16 v[76:79], v[154:157], v[216:219], v[76:79]
	v_mfma_f32_16x16x32_bf16 v[68:71], v[162:165], v[216:219], v[68:71]
	v_mfma_f32_16x16x32_bf16 v[124:127], v[158:161], v[196:199], v[124:127]
	v_mfma_f32_16x16x32_bf16 v[116:119], v[166:169], v[196:199], v[116:119]
	v_mfma_f32_16x16x32_bf16 v[108:111], v[158:161], v[204:207], v[108:111]
	v_mfma_f32_16x16x32_bf16 v[100:103], v[166:169], v[204:207], v[100:103]
	v_mfma_f32_16x16x32_bf16 v[92:95], v[158:161], v[212:215], v[92:95]
	v_mfma_f32_16x16x32_bf16 v[84:87], v[166:169], v[212:215], v[84:87]
	v_mfma_f32_16x16x32_bf16 v[76:79], v[158:161], v[220:223], v[76:79]
	v_mfma_f32_16x16x32_bf16 v[68:71], v[166:169], v[220:223], v[68:71]
	v_mfma_f32_16x16x32_bf16 v[120:123], v[170:173], v[192:195], v[120:123]
	v_mfma_f32_16x16x32_bf16 v[112:115], v[184:187], v[192:195], v[112:115]
	v_mfma_f32_16x16x32_bf16 v[104:107], v[170:173], v[200:203], v[104:107]
	v_mfma_f32_16x16x32_bf16 v[96:99], v[184:187], v[200:203], v[96:99]
	v_mfma_f32_16x16x32_bf16 v[88:91], v[170:173], v[208:211], v[88:91]
	v_mfma_f32_16x16x32_bf16 v[80:83], v[184:187], v[208:211], v[80:83]
	v_mfma_f32_16x16x32_bf16 v[72:75], v[170:173], v[216:219], v[72:75]
	v_mfma_f32_16x16x32_bf16 v[64:67], v[184:187], v[216:219], v[64:67]
	v_mfma_f32_16x16x32_bf16 v[120:123], v[174:177], v[196:199], v[120:123]
	v_mfma_f32_16x16x32_bf16 v[112:115], v[188:191], v[196:199], v[112:115]
	v_mfma_f32_16x16x32_bf16 v[104:107], v[174:177], v[204:207], v[104:107]
	v_mfma_f32_16x16x32_bf16 v[96:99], v[188:191], v[204:207], v[96:99]
	v_mfma_f32_16x16x32_bf16 v[88:91], v[174:177], v[212:215], v[88:91]
	v_mfma_f32_16x16x32_bf16 v[80:83], v[188:191], v[212:215], v[80:83]
	v_mfma_f32_16x16x32_bf16 v[72:75], v[174:177], v[220:223], v[72:75]
	v_mfma_f32_16x16x32_bf16 v[64:67], v[188:191], v[220:223], v[64:67]
	s_barrier
	s_add_i32 s47, s36, s28
	v_lshl_add_u64 v[178:179], s[22:23], 0, v[132:133]
	s_mov_b32 m0, s47
	ds_read_b128 v[192:195], v153 offset:16384
	ds_read_b128 v[196:199], v153 offset:17408
	ds_read_b128 v[200:203], v153 offset:18432
	ds_read_b128 v[204:207], v153 offset:19456
	ds_read_b128 v[208:211], v153 offset:20480
	ds_read_b128 v[212:215], v153 offset:21504
	ds_read_b128 v[216:219], v153 offset:22528
	ds_read_b128 v[220:223], v153 offset:23552
	global_load_lds_dwordx4 v[178:179], off
	s_add_i32 m0, s47, 0x2000
	s_add_u32 s48, s22, 0x40000
	v_lshl_add_u64 v[224:225], s[22:23], 0, v[128:129]
	s_addc_u32 s49, s23, 0
	s_add_i32 s47, s37, s28
	global_load_lds_dwordx4 v[224:225], off
	v_lshl_add_u64 v[226:227], s[48:49], 0, v[132:133]
	s_mov_b32 m0, s47
	global_load_lds_dwordx4 v[226:227], off
	v_lshl_add_u64 v[226:227], s[48:49], 0, v[128:129]
	s_add_i32 m0, s47, 0x2000
	s_nop 0
	global_load_lds_dwordx4 v[226:227], off
	s_waitcnt vmcnt(6)
	s_waitcnt lgkmcnt(0)
	s_barrier
	s_waitcnt lgkmcnt(0)
	v_mfma_f32_16x16x32_bf16 v[60:63], v[154:157], v[192:195], v[60:63]
	v_mfma_f32_16x16x32_bf16 v[52:55], v[162:165], v[192:195], v[52:55]
	v_mfma_f32_16x16x32_bf16 v[44:47], v[154:157], v[200:203], v[44:47]
	v_mfma_f32_16x16x32_bf16 v[36:39], v[162:165], v[200:203], v[36:39]
	v_mfma_f32_16x16x32_bf16 v[28:31], v[154:157], v[208:211], v[28:31]
	v_mfma_f32_16x16x32_bf16 v[20:23], v[162:165], v[208:211], v[20:23]
	v_mfma_f32_16x16x32_bf16 v[12:15], v[154:157], v[216:219], v[12:15]
	v_mfma_f32_16x16x32_bf16 v[4:7], v[162:165], v[216:219], v[4:7]
	v_mfma_f32_16x16x32_bf16 v[60:63], v[158:161], v[196:199], v[60:63]
	v_mfma_f32_16x16x32_bf16 v[52:55], v[166:169], v[196:199], v[52:55]
	v_mfma_f32_16x16x32_bf16 v[44:47], v[158:161], v[204:207], v[44:47]
	v_mfma_f32_16x16x32_bf16 v[36:39], v[166:169], v[204:207], v[36:39]
	v_mfma_f32_16x16x32_bf16 v[28:31], v[158:161], v[212:215], v[28:31]
	v_mfma_f32_16x16x32_bf16 v[20:23], v[166:169], v[212:215], v[20:23]
	v_mfma_f32_16x16x32_bf16 v[12:15], v[158:161], v[220:223], v[12:15]
	v_mfma_f32_16x16x32_bf16 v[4:7], v[166:169], v[220:223], v[4:7]
	v_mfma_f32_16x16x32_bf16 v[56:59], v[170:173], v[192:195], v[56:59]
	v_mfma_f32_16x16x32_bf16 v[48:51], v[184:187], v[192:195], v[48:51]
	v_mfma_f32_16x16x32_bf16 v[40:43], v[170:173], v[200:203], v[40:43]
	v_mfma_f32_16x16x32_bf16 v[32:35], v[184:187], v[200:203], v[32:35]
	v_mfma_f32_16x16x32_bf16 v[24:27], v[170:173], v[208:211], v[24:27]
	v_mfma_f32_16x16x32_bf16 v[16:19], v[184:187], v[208:211], v[16:19]
	v_mfma_f32_16x16x32_bf16 v[8:11], v[170:173], v[216:219], v[8:11]
	v_mfma_f32_16x16x32_bf16 v[0:3], v[184:187], v[216:219], v[0:3]
	v_mfma_f32_16x16x32_bf16 v[56:59], v[174:177], v[196:199], v[56:59]
	v_mfma_f32_16x16x32_bf16 v[48:51], v[188:191], v[196:199], v[48:51]
	v_mfma_f32_16x16x32_bf16 v[40:43], v[174:177], v[204:207], v[40:43]
	v_mfma_f32_16x16x32_bf16 v[32:35], v[188:191], v[204:207], v[32:35]
	v_mfma_f32_16x16x32_bf16 v[24:27], v[174:177], v[212:215], v[24:27]
	v_mfma_f32_16x16x32_bf16 v[16:19], v[188:191], v[212:215], v[16:19]
	v_mfma_f32_16x16x32_bf16 v[8:11], v[174:177], v[220:223], v[8:11]
	v_mfma_f32_16x16x32_bf16 v[0:3], v[188:191], v[220:223], v[0:3]
	s_barrier
	s_add_i32 s47, 0, 0x18000
	s_add_i32 s48, 0, 0x1c000
	v_add_u32_e32 v166, s47, v145
	v_add_u32_e32 v180, s48, v145
	ds_read_b128 v[154:157], v166
	ds_read_b128 v[158:161], v166 offset:1024
	ds_read_b128 v[162:165], v166 offset:2048
	ds_read_b128 v[166:169], v166 offset:3072
	ds_read_b128 v[170:173], v180
	ds_read_b128 v[174:177], v180 offset:1024
	ds_read_b128 v[184:187], v180 offset:2048
	ds_read_b128 v[188:191], v180 offset:3072
	v_lshl_add_u64 v[226:227], s[24:25], 0, v[134:135]
	s_mov_b32 m0, s19
	v_lshl_add_u64 v[228:229], s[24:25], 0, v[130:131]
	global_load_lds_dwordx4 v[226:227], off
	s_mov_b32 m0, s30
	s_nop 0
	global_load_lds_dwordx4 v[228:229], off
	s_add_u32 s24, s24, 0x40000
	s_addc_u32 s25, s25, 0
	s_mov_b32 m0, s31
	v_lshl_add_u64 v[230:231], s[24:25], 0, v[134:135]
	ds_read_b128 v[192:195], v153 offset:32768
	ds_read_b128 v[196:199], v153 offset:33792
	ds_read_b128 v[200:203], v153 offset:34816
	ds_read_b128 v[204:207], v153 offset:35840
	ds_read_b128 v[208:211], v153 offset:36864
	ds_read_b128 v[212:215], v153 offset:37888
	ds_read_b128 v[216:219], v153 offset:38912
	ds_read_b128 v[220:223], v153 offset:39936
	global_load_lds_dwordx4 v[230:231], off
	v_lshl_add_u64 v[230:231], s[24:25], 0, v[130:131]
	s_mov_b32 m0, s33
	s_nop 0
	global_load_lds_dwordx4 v[230:231], off
	s_waitcnt vmcnt(8)
	s_waitcnt lgkmcnt(0)
	s_barrier
	s_waitcnt lgkmcnt(0)
	v_mfma_f32_16x16x32_bf16 v[124:127], v[154:157], v[192:195], v[124:127]
	v_mfma_f32_16x16x32_bf16 v[116:119], v[162:165], v[192:195], v[116:119]
	v_mfma_f32_16x16x32_bf16 v[108:111], v[154:157], v[200:203], v[108:111]
	v_mfma_f32_16x16x32_bf16 v[100:103], v[162:165], v[200:203], v[100:103]
	v_mfma_f32_16x16x32_bf16 v[92:95], v[154:157], v[208:211], v[92:95]
	v_mfma_f32_16x16x32_bf16 v[84:87], v[162:165], v[208:211], v[84:87]
	v_mfma_f32_16x16x32_bf16 v[76:79], v[154:157], v[216:219], v[76:79]
	v_mfma_f32_16x16x32_bf16 v[68:71], v[162:165], v[216:219], v[68:71]
	v_mfma_f32_16x16x32_bf16 v[124:127], v[158:161], v[196:199], v[124:127]
	v_mfma_f32_16x16x32_bf16 v[116:119], v[166:169], v[196:199], v[116:119]
	v_mfma_f32_16x16x32_bf16 v[108:111], v[158:161], v[204:207], v[108:111]
	v_mfma_f32_16x16x32_bf16 v[100:103], v[166:169], v[204:207], v[100:103]
	v_mfma_f32_16x16x32_bf16 v[92:95], v[158:161], v[212:215], v[92:95]
	v_mfma_f32_16x16x32_bf16 v[84:87], v[166:169], v[212:215], v[84:87]
	v_mfma_f32_16x16x32_bf16 v[76:79], v[158:161], v[220:223], v[76:79]
	v_mfma_f32_16x16x32_bf16 v[68:71], v[166:169], v[220:223], v[68:71]
	v_mfma_f32_16x16x32_bf16 v[120:123], v[170:173], v[192:195], v[120:123]
	v_mfma_f32_16x16x32_bf16 v[112:115], v[184:187], v[192:195], v[112:115]
	v_mfma_f32_16x16x32_bf16 v[104:107], v[170:173], v[200:203], v[104:107]
	v_mfma_f32_16x16x32_bf16 v[96:99], v[184:187], v[200:203], v[96:99]
	v_mfma_f32_16x16x32_bf16 v[88:91], v[170:173], v[208:211], v[88:91]
	v_mfma_f32_16x16x32_bf16 v[80:83], v[184:187], v[208:211], v[80:83]
	v_mfma_f32_16x16x32_bf16 v[72:75], v[170:173], v[216:219], v[72:75]
	v_mfma_f32_16x16x32_bf16 v[64:67], v[184:187], v[216:219], v[64:67]
	v_mfma_f32_16x16x32_bf16 v[120:123], v[174:177], v[196:199], v[120:123]
	v_mfma_f32_16x16x32_bf16 v[112:115], v[188:191], v[196:199], v[112:115]
	v_mfma_f32_16x16x32_bf16 v[104:107], v[174:177], v[204:207], v[104:107]
	v_mfma_f32_16x16x32_bf16 v[96:99], v[188:191], v[204:207], v[96:99]
	v_mfma_f32_16x16x32_bf16 v[88:91], v[174:177], v[212:215], v[88:91]
	v_mfma_f32_16x16x32_bf16 v[80:83], v[188:191], v[212:215], v[80:83]
	v_mfma_f32_16x16x32_bf16 v[72:75], v[174:177], v[220:223], v[72:75]
	v_mfma_f32_16x16x32_bf16 v[64:67], v[188:191], v[220:223], v[64:67]
	s_barrier
	s_add_i32 s24, s47, s28
	v_lshl_add_u64 v[178:179], v[178:179], 0, s[6:7]
	s_mov_b32 m0, s24
	ds_read_b128 v[192:195], v153 offset:49152
	ds_read_b128 v[196:199], v153 offset:50176
	ds_read_b128 v[200:203], v153 offset:51200
	ds_read_b128 v[204:207], v153 offset:52224
	ds_read_b128 v[208:211], v153 offset:53248
	ds_read_b128 v[212:215], v153 offset:54272
	ds_read_b128 v[216:219], v153 offset:55296
	ds_read_b128 v[220:223], v153 offset:56320
	global_load_lds_dwordx4 v[178:179], off
	s_add_i32 m0, s24, 0x2000
	s_add_u32 s22, s22, 0x40080
	v_lshl_add_u64 v[178:179], v[224:225], 0, s[6:7]
	s_addc_u32 s23, s23, 0
	s_add_i32 s24, s48, s28
	global_load_lds_dwordx4 v[178:179], off
	v_lshl_add_u64 v[178:179], s[22:23], 0, v[132:133]
	s_mov_b32 m0, s24
	s_nop 0
	global_load_lds_dwordx4 v[178:179], off
	v_lshl_add_u64 v[178:179], s[22:23], 0, v[128:129]
	s_add_i32 m0, s24, 0x2000
	s_nop 0
	global_load_lds_dwordx4 v[178:179], off
	s_waitcnt vmcnt(6)
	s_waitcnt lgkmcnt(0)
	s_barrier
	s_waitcnt lgkmcnt(0)
	v_mfma_f32_16x16x32_bf16 v[60:63], v[154:157], v[192:195], v[60:63]
	v_mfma_f32_16x16x32_bf16 v[52:55], v[162:165], v[192:195], v[52:55]
	v_mfma_f32_16x16x32_bf16 v[44:47], v[154:157], v[200:203], v[44:47]
	v_mfma_f32_16x16x32_bf16 v[36:39], v[162:165], v[200:203], v[36:39]
	v_mfma_f32_16x16x32_bf16 v[28:31], v[154:157], v[208:211], v[28:31]
	v_mfma_f32_16x16x32_bf16 v[20:23], v[162:165], v[208:211], v[20:23]
	v_mfma_f32_16x16x32_bf16 v[12:15], v[154:157], v[216:219], v[12:15]
	v_mfma_f32_16x16x32_bf16 v[4:7], v[162:165], v[216:219], v[4:7]
	v_mfma_f32_16x16x32_bf16 v[60:63], v[158:161], v[196:199], v[60:63]
	v_mfma_f32_16x16x32_bf16 v[52:55], v[166:169], v[196:199], v[52:55]
	v_mfma_f32_16x16x32_bf16 v[44:47], v[158:161], v[204:207], v[44:47]
	v_mfma_f32_16x16x32_bf16 v[36:39], v[166:169], v[204:207], v[36:39]
	v_mfma_f32_16x16x32_bf16 v[28:31], v[158:161], v[212:215], v[28:31]
	v_mfma_f32_16x16x32_bf16 v[20:23], v[166:169], v[212:215], v[20:23]
	v_mfma_f32_16x16x32_bf16 v[12:15], v[158:161], v[220:223], v[12:15]
	v_mfma_f32_16x16x32_bf16 v[4:7], v[166:169], v[220:223], v[4:7]
	v_mfma_f32_16x16x32_bf16 v[56:59], v[170:173], v[192:195], v[56:59]
	v_mfma_f32_16x16x32_bf16 v[48:51], v[184:187], v[192:195], v[48:51]
	v_mfma_f32_16x16x32_bf16 v[40:43], v[170:173], v[200:203], v[40:43]
	v_mfma_f32_16x16x32_bf16 v[32:35], v[184:187], v[200:203], v[32:35]
	v_mfma_f32_16x16x32_bf16 v[24:27], v[170:173], v[208:211], v[24:27]
	v_mfma_f32_16x16x32_bf16 v[16:19], v[184:187], v[208:211], v[16:19]
	v_mfma_f32_16x16x32_bf16 v[8:11], v[170:173], v[216:219], v[8:11]
	v_mfma_f32_16x16x32_bf16 v[0:3], v[184:187], v[216:219], v[0:3]
	v_mfma_f32_16x16x32_bf16 v[56:59], v[174:177], v[196:199], v[56:59]
	v_mfma_f32_16x16x32_bf16 v[48:51], v[188:191], v[196:199], v[48:51]
	v_mfma_f32_16x16x32_bf16 v[40:43], v[174:177], v[204:207], v[40:43]
	v_mfma_f32_16x16x32_bf16 v[32:35], v[188:191], v[204:207], v[32:35]
	v_mfma_f32_16x16x32_bf16 v[24:27], v[174:177], v[212:215], v[24:27]
	v_mfma_f32_16x16x32_bf16 v[16:19], v[188:191], v[212:215], v[16:19]
	v_mfma_f32_16x16x32_bf16 v[8:11], v[174:177], v[220:223], v[8:11]
	v_mfma_f32_16x16x32_bf16 v[0:3], v[188:191], v[220:223], v[0:3]
	s_barrier
	v_lshl_add_u64 v[178:179], v[226:227], 0, s[6:7]
	s_mov_b32 m0, s34
	s_nop 0
	global_load_lds_dwordx4 v[178:179], off
	v_lshl_add_u64 v[178:179], v[228:229], 0, s[6:7]
	s_mov_b32 m0, s35
	s_nop 0
	global_load_lds_dwordx4 v[178:179], off
	s_add_i32 s46, s46, 2
	s_add_u32 s20, s20, 0x100
	s_addc_u32 s21, s21, 0
	s_add_u32 s44, s44, 0x100
	s_addc_u32 s45, s45, 0
	s_cmp_gt_u32 s46, 13
	s_cbranch_scc0 .LBB0_1379
	s_and_b64 vcc, exec, s[8:9]
	s_cbranch_vccz .LBB0_1382
	s_barrier

.LBB0_1461:
	ds_read_b128 v[144:147], v151
	ds_read_b128 v[156:159], v151 offset:1024
	ds_read_b128 v[160:163], v151 offset:2048
	ds_read_b128 v[164:167], v151 offset:3072
	ds_read_b128 v[168:171], v152
	ds_read_b128 v[172:175], v152 offset:1024
	ds_read_b128 v[176:179], v152 offset:2048
	ds_read_b128 v[182:185], v152 offset:3072
	s_add_u32 s20, s18, 0x100
	s_addc_u32 s21, s19, 0
	s_cmp_eq_u32 s45, 40
	s_cselect_b32 s25, s7, s21
	s_cselect_b32 s24, s6, s20
	s_cselect_b32 s23, s17, s44
	s_cselect_b32 s22, s16, s43
	v_lshl_add_u64 v[218:219], s[18:19], 0, v[136:137]
	s_add_i32 m0, s29, 0xc000
	ds_read_b128 v[186:189], v153
	ds_read_b128 v[190:193], v153 offset:1024
	ds_read_b128 v[194:197], v153 offset:2048
	ds_read_b128 v[198:201], v153 offset:3072
	ds_read_b128 v[202:205], v153 offset:4096
	ds_read_b128 v[206:209], v153 offset:5120
	ds_read_b128 v[210:213], v153 offset:6144
	ds_read_b128 v[214:217], v153 offset:7168
	global_load_lds_dwordx4 v[218:219], off
	v_lshl_add_u64 v[218:219], s[18:19], 0, v[138:139]
	s_add_i32 m0, s29, 0xe000
	s_nop 0
	global_load_lds_dwordx4 v[218:219], off
	s_waitcnt vmcnt(8)
	s_waitcnt lgkmcnt(0)
	s_barrier
	s_waitcnt lgkmcnt(0)
	v_mfma_f32_16x16x32_bf16 v[124:127], v[144:147], v[186:189], v[124:127]
	v_mfma_f32_16x16x32_bf16 v[120:123], v[160:163], v[186:189], v[120:123]
	v_mfma_f32_16x16x32_bf16 v[108:111], v[144:147], v[194:197], v[108:111]
	v_mfma_f32_16x16x32_bf16 v[104:107], v[160:163], v[194:197], v[104:107]
	v_mfma_f32_16x16x32_bf16 v[92:95], v[144:147], v[202:205], v[92:95]
	v_mfma_f32_16x16x32_bf16 v[88:91], v[160:163], v[202:205], v[88:91]
	v_mfma_f32_16x16x32_bf16 v[76:79], v[144:147], v[210:213], v[76:79]
	v_mfma_f32_16x16x32_bf16 v[72:75], v[160:163], v[210:213], v[72:75]
	v_mfma_f32_16x16x32_bf16 v[124:127], v[156:159], v[190:193], v[124:127]
	v_mfma_f32_16x16x32_bf16 v[120:123], v[164:167], v[190:193], v[120:123]
	v_mfma_f32_16x16x32_bf16 v[108:111], v[156:159], v[198:201], v[108:111]
	v_mfma_f32_16x16x32_bf16 v[104:107], v[164:167], v[198:201], v[104:107]
	v_mfma_f32_16x16x32_bf16 v[92:95], v[156:159], v[206:209], v[92:95]
	v_mfma_f32_16x16x32_bf16 v[88:91], v[164:167], v[206:209], v[88:91]
	v_mfma_f32_16x16x32_bf16 v[76:79], v[156:159], v[214:217], v[76:79]
	v_mfma_f32_16x16x32_bf16 v[72:75], v[164:167], v[214:217], v[72:75]
	v_mfma_f32_16x16x32_bf16 v[116:119], v[168:171], v[186:189], v[116:119]
	v_mfma_f32_16x16x32_bf16 v[112:115], v[176:179], v[186:189], v[112:115]
	v_mfma_f32_16x16x32_bf16 v[100:103], v[168:171], v[194:197], v[100:103]
	v_mfma_f32_16x16x32_bf16 v[96:99], v[176:179], v[194:197], v[96:99]
	v_mfma_f32_16x16x32_bf16 v[84:87], v[168:171], v[202:205], v[84:87]
	v_mfma_f32_16x16x32_bf16 v[80:83], v[176:179], v[202:205], v[80:83]
	v_mfma_f32_16x16x32_bf16 v[68:71], v[168:171], v[210:213], v[68:71]
	v_mfma_f32_16x16x32_bf16 v[64:67], v[176:179], v[210:213], v[64:67]
	v_mfma_f32_16x16x32_bf16 v[116:119], v[172:175], v[190:193], v[116:119]
	v_mfma_f32_16x16x32_bf16 v[112:115], v[182:185], v[190:193], v[112:115]
	v_mfma_f32_16x16x32_bf16 v[100:103], v[172:175], v[198:201], v[100:103]
	v_mfma_f32_16x16x32_bf16 v[96:99], v[182:185], v[198:201], v[96:99]
	v_mfma_f32_16x16x32_bf16 v[84:87], v[172:175], v[206:209], v[84:87]
	v_mfma_f32_16x16x32_bf16 v[80:83], v[182:185], v[206:209], v[80:83]
	v_mfma_f32_16x16x32_bf16 v[68:71], v[172:175], v[214:217], v[68:71]
	v_mfma_f32_16x16x32_bf16 v[64:67], v[182:185], v[214:217], v[64:67]
	s_barrier
	s_add_i32 s18, s37, s28
	v_lshl_add_u64 v[218:219], s[22:23], 0, v[130:131]
	s_mov_b32 m0, s18
	ds_read_b128 v[186:189], v153 offset:16384
	ds_read_b128 v[190:193], v153 offset:17408
	ds_read_b128 v[194:197], v153 offset:18432
	ds_read_b128 v[198:201], v153 offset:19456
	ds_read_b128 v[202:205], v153 offset:20480
	ds_read_b128 v[206:209], v153 offset:21504
	ds_read_b128 v[210:213], v153 offset:22528
	ds_read_b128 v[214:217], v153 offset:23552
	global_load_lds_dwordx4 v[218:219], off
	s_add_i32 m0, s18, 0x2000
	s_add_u32 s18, s22, 0xb0000
	v_lshl_add_u64 v[220:221], s[22:23], 0, v[134:135]
	s_addc_u32 s19, s23, 0
	s_add_i32 s46, s38, s28
	global_load_lds_dwordx4 v[220:221], off
	v_lshl_add_u64 v[222:223], s[18:19], 0, v[130:131]
	s_mov_b32 m0, s46
	global_load_lds_dwordx4 v[222:223], off
	v_lshl_add_u64 v[222:223], s[18:19], 0, v[134:135]
	s_add_i32 m0, s46, 0x2000
	s_nop 0
	global_load_lds_dwordx4 v[222:223], off
	s_waitcnt vmcnt(6)
	s_waitcnt lgkmcnt(0)
	s_barrier
	s_waitcnt lgkmcnt(0)
	v_mfma_f32_16x16x32_bf16 v[60:63], v[144:147], v[186:189], v[60:63]
	v_mfma_f32_16x16x32_bf16 v[56:59], v[160:163], v[186:189], v[56:59]
	v_mfma_f32_16x16x32_bf16 v[44:47], v[144:147], v[194:197], v[44:47]
	v_mfma_f32_16x16x32_bf16 v[40:43], v[160:163], v[194:197], v[40:43]
	v_mfma_f32_16x16x32_bf16 v[28:31], v[144:147], v[202:205], v[28:31]
	v_mfma_f32_16x16x32_bf16 v[24:27], v[160:163], v[202:205], v[24:27]
	v_mfma_f32_16x16x32_bf16 v[12:15], v[144:147], v[210:213], v[12:15]
	v_mfma_f32_16x16x32_bf16 v[8:11], v[160:163], v[210:213], v[8:11]
	v_mfma_f32_16x16x32_bf16 v[60:63], v[156:159], v[190:193], v[60:63]
	v_mfma_f32_16x16x32_bf16 v[56:59], v[164:167], v[190:193], v[56:59]
	v_mfma_f32_16x16x32_bf16 v[44:47], v[156:159], v[198:201], v[44:47]
	v_mfma_f32_16x16x32_bf16 v[40:43], v[164:167], v[198:201], v[40:43]
	v_mfma_f32_16x16x32_bf16 v[28:31], v[156:159], v[206:209], v[28:31]
	v_mfma_f32_16x16x32_bf16 v[24:27], v[164:167], v[206:209], v[24:27]
	v_mfma_f32_16x16x32_bf16 v[12:15], v[156:159], v[214:217], v[12:15]
	v_mfma_f32_16x16x32_bf16 v[8:11], v[164:167], v[214:217], v[8:11]
	v_mfma_f32_16x16x32_bf16 v[52:55], v[168:171], v[186:189], v[52:55]
	v_mfma_f32_16x16x32_bf16 v[48:51], v[176:179], v[186:189], v[48:51]
	v_mfma_f32_16x16x32_bf16 v[36:39], v[168:171], v[194:197], v[36:39]
	v_mfma_f32_16x16x32_bf16 v[32:35], v[176:179], v[194:197], v[32:35]
	v_mfma_f32_16x16x32_bf16 v[20:23], v[168:171], v[202:205], v[20:23]
	v_mfma_f32_16x16x32_bf16 v[16:19], v[176:179], v[202:205], v[16:19]
	v_mfma_f32_16x16x32_bf16 v[4:7], v[168:171], v[210:213], v[4:7]
	v_mfma_f32_16x16x32_bf16 v[0:3], v[176:179], v[210:213], v[0:3]
	v_mfma_f32_16x16x32_bf16 v[52:55], v[172:175], v[190:193], v[52:55]
	v_mfma_f32_16x16x32_bf16 v[48:51], v[182:185], v[190:193], v[48:51]
	v_mfma_f32_16x16x32_bf16 v[36:39], v[172:175], v[198:201], v[36:39]
	v_mfma_f32_16x16x32_bf16 v[32:35], v[182:185], v[198:201], v[32:35]
	v_mfma_f32_16x16x32_bf16 v[20:23], v[172:175], v[206:209], v[20:23]
	v_mfma_f32_16x16x32_bf16 v[16:19], v[182:185], v[206:209], v[16:19]
	v_mfma_f32_16x16x32_bf16 v[4:7], v[172:175], v[214:217], v[4:7]
	v_mfma_f32_16x16x32_bf16 v[0:3], v[182:185], v[214:217], v[0:3]
	s_barrier
	s_add_i32 s46, 0, 0x18000
	v_add_u32_e32 v155, s46, v149
	s_add_i32 s47, 0, 0x1c000
	ds_read_b128 v[144:147], v155
	ds_read_b128 v[156:159], v155 offset:1024
	ds_read_b128 v[160:163], v155 offset:2048
	ds_read_b128 v[164:167], v155 offset:3072
	v_add_u32_e32 v155, s47, v149
	ds_read_b128 v[168:171], v155
	ds_read_b128 v[172:175], v155 offset:1024
	ds_read_b128 v[176:179], v155 offset:2048
	ds_read_b128 v[182:185], v155 offset:3072
	s_add_u32 s18, s24, 0xb0000
	s_addc_u32 s19, s25, 0
	v_lshl_add_u64 v[222:223], s[24:25], 0, v[128:129]
	s_mov_b32 m0, s29
	v_lshl_add_u64 v[224:225], s[24:25], 0, v[132:133]
	global_load_lds_dwordx4 v[222:223], off
	s_mov_b32 m0, s30
	s_nop 0
	global_load_lds_dwordx4 v[224:225], off
	s_mov_b32 m0, s31
	v_lshl_add_u64 v[226:227], s[18:19], 0, v[128:129]
	ds_read_b128 v[186:189], v153 offset:32768
	ds_read_b128 v[190:193], v153 offset:33792
	ds_read_b128 v[194:197], v153 offset:34816
	ds_read_b128 v[198:201], v153 offset:35840
	ds_read_b128 v[202:205], v153 offset:36864
	ds_read_b128 v[206:209], v153 offset:37888
	ds_read_b128 v[210:213], v153 offset:38912
	ds_read_b128 v[214:217], v153 offset:39936
	global_load_lds_dwordx4 v[226:227], off
	v_lshl_add_u64 v[226:227], s[18:19], 0, v[132:133]
	s_mov_b32 m0, s33
	s_nop 0
	global_load_lds_dwordx4 v[226:227], off
	s_waitcnt vmcnt(8)
	s_waitcnt lgkmcnt(0)
	s_barrier
	s_waitcnt lgkmcnt(0)
	v_mfma_f32_16x16x32_bf16 v[124:127], v[144:147], v[186:189], v[124:127]
	v_mfma_f32_16x16x32_bf16 v[120:123], v[160:163], v[186:189], v[120:123]
	v_mfma_f32_16x16x32_bf16 v[108:111], v[144:147], v[194:197], v[108:111]
	v_mfma_f32_16x16x32_bf16 v[104:107], v[160:163], v[194:197], v[104:107]
	v_mfma_f32_16x16x32_bf16 v[92:95], v[144:147], v[202:205], v[92:95]
	v_mfma_f32_16x16x32_bf16 v[88:91], v[160:163], v[202:205], v[88:91]
	v_mfma_f32_16x16x32_bf16 v[76:79], v[144:147], v[210:213], v[76:79]
	v_mfma_f32_16x16x32_bf16 v[72:75], v[160:163], v[210:213], v[72:75]
	v_mfma_f32_16x16x32_bf16 v[124:127], v[156:159], v[190:193], v[124:127]
	v_mfma_f32_16x16x32_bf16 v[120:123], v[164:167], v[190:193], v[120:123]
	v_mfma_f32_16x16x32_bf16 v[108:111], v[156:159], v[198:201], v[108:111]
	v_mfma_f32_16x16x32_bf16 v[104:107], v[164:167], v[198:201], v[104:107]
	v_mfma_f32_16x16x32_bf16 v[92:95], v[156:159], v[206:209], v[92:95]
	v_mfma_f32_16x16x32_bf16 v[88:91], v[164:167], v[206:209], v[88:91]
	v_mfma_f32_16x16x32_bf16 v[76:79], v[156:159], v[214:217], v[76:79]
	v_mfma_f32_16x16x32_bf16 v[72:75], v[164:167], v[214:217], v[72:75]
	v_mfma_f32_16x16x32_bf16 v[116:119], v[168:171], v[186:189], v[116:119]
	v_mfma_f32_16x16x32_bf16 v[112:115], v[176:179], v[186:189], v[112:115]
	v_mfma_f32_16x16x32_bf16 v[100:103], v[168:171], v[194:197], v[100:103]
	v_mfma_f32_16x16x32_bf16 v[96:99], v[176:179], v[194:197], v[96:99]
	v_mfma_f32_16x16x32_bf16 v[84:87], v[168:171], v[202:205], v[84:87]
	v_mfma_f32_16x16x32_bf16 v[80:83], v[176:179], v[202:205], v[80:83]
	v_mfma_f32_16x16x32_bf16 v[68:71], v[168:171], v[210:213], v[68:71]
	v_mfma_f32_16x16x32_bf16 v[64:67], v[176:179], v[210:213], v[64:67]
	v_mfma_f32_16x16x32_bf16 v[116:119], v[172:175], v[190:193], v[116:119]
	v_mfma_f32_16x16x32_bf16 v[112:115], v[182:185], v[190:193], v[112:115]
	v_mfma_f32_16x16x32_bf16 v[100:103], v[172:175], v[198:201], v[100:103]
	v_mfma_f32_16x16x32_bf16 v[96:99], v[182:185], v[198:201], v[96:99]
	v_mfma_f32_16x16x32_bf16 v[84:87], v[172:175], v[206:209], v[84:87]
	v_mfma_f32_16x16x32_bf16 v[80:83], v[182:185], v[206:209], v[80:83]
	v_mfma_f32_16x16x32_bf16 v[68:71], v[172:175], v[214:217], v[68:71]
	v_mfma_f32_16x16x32_bf16 v[64:67], v[182:185], v[214:217], v[64:67]
	s_barrier
	s_add_i32 s18, s46, s28
	v_lshl_add_u64 v[218:219], v[218:219], 0, s[12:13]
	s_mov_b32 m0, s18
	ds_read_b128 v[186:189], v153 offset:49152
	ds_read_b128 v[190:193], v153 offset:50176
	ds_read_b128 v[194:197], v153 offset:51200
	ds_read_b128 v[198:201], v153 offset:52224
	ds_read_b128 v[202:205], v153 offset:53248
	ds_read_b128 v[206:209], v153 offset:54272
	ds_read_b128 v[210:213], v153 offset:55296
	ds_read_b128 v[214:217], v153 offset:56320
	global_load_lds_dwordx4 v[218:219], off
	s_add_i32 m0, s18, 0x2000
	s_add_u32 s18, s22, 0xb0080
	v_lshl_add_u64 v[218:219], v[220:221], 0, s[12:13]
	s_addc_u32 s19, s23, 0
	s_add_i32 s22, s47, s28
	global_load_lds_dwordx4 v[218:219], off
	v_lshl_add_u64 v[218:219], s[18:19], 0, v[130:131]
	s_mov_b32 m0, s22
	s_nop 0
	global_load_lds_dwordx4 v[218:219], off
	v_lshl_add_u64 v[218:219], s[18:19], 0, v[134:135]
	s_add_i32 m0, s22, 0x2000
	s_nop 0
	global_load_lds_dwordx4 v[218:219], off
	s_waitcnt vmcnt(6)
	s_waitcnt lgkmcnt(0)
	s_barrier
	s_waitcnt lgkmcnt(0)
	v_mfma_f32_16x16x32_bf16 v[60:63], v[144:147], v[186:189], v[60:63]
	v_mfma_f32_16x16x32_bf16 v[56:59], v[160:163], v[186:189], v[56:59]
	v_mfma_f32_16x16x32_bf16 v[44:47], v[144:147], v[194:197], v[44:47]
	v_mfma_f32_16x16x32_bf16 v[40:43], v[160:163], v[194:197], v[40:43]
	v_mfma_f32_16x16x32_bf16 v[28:31], v[144:147], v[202:205], v[28:31]
	v_mfma_f32_16x16x32_bf16 v[24:27], v[160:163], v[202:205], v[24:27]
	v_mfma_f32_16x16x32_bf16 v[12:15], v[144:147], v[210:213], v[12:15]
	v_mfma_f32_16x16x32_bf16 v[8:11], v[160:163], v[210:213], v[8:11]
	v_mfma_f32_16x16x32_bf16 v[60:63], v[156:159], v[190:193], v[60:63]
	v_mfma_f32_16x16x32_bf16 v[56:59], v[164:167], v[190:193], v[56:59]
	v_mfma_f32_16x16x32_bf16 v[44:47], v[156:159], v[198:201], v[44:47]
	v_mfma_f32_16x16x32_bf16 v[40:43], v[164:167], v[198:201], v[40:43]
	v_mfma_f32_16x16x32_bf16 v[28:31], v[156:159], v[206:209], v[28:31]
	v_mfma_f32_16x16x32_bf16 v[24:27], v[164:167], v[206:209], v[24:27]
	v_mfma_f32_16x16x32_bf16 v[12:15], v[156:159], v[214:217], v[12:15]
	v_mfma_f32_16x16x32_bf16 v[8:11], v[164:167], v[214:217], v[8:11]
	v_mfma_f32_16x16x32_bf16 v[52:55], v[168:171], v[186:189], v[52:55]
	v_mfma_f32_16x16x32_bf16 v[48:51], v[176:179], v[186:189], v[48:51]
	v_mfma_f32_16x16x32_bf16 v[36:39], v[168:171], v[194:197], v[36:39]
	v_mfma_f32_16x16x32_bf16 v[32:35], v[176:179], v[194:197], v[32:35]
	v_mfma_f32_16x16x32_bf16 v[20:23], v[168:171], v[202:205], v[20:23]
	v_mfma_f32_16x16x32_bf16 v[16:19], v[176:179], v[202:205], v[16:19]
	v_mfma_f32_16x16x32_bf16 v[4:7], v[168:171], v[210:213], v[4:7]
	v_mfma_f32_16x16x32_bf16 v[0:3], v[176:179], v[210:213], v[0:3]
	v_mfma_f32_16x16x32_bf16 v[52:55], v[172:175], v[190:193], v[52:55]
	v_mfma_f32_16x16x32_bf16 v[48:51], v[182:185], v[190:193], v[48:51]
	v_mfma_f32_16x16x32_bf16 v[36:39], v[172:175], v[198:201], v[36:39]
	v_mfma_f32_16x16x32_bf16 v[32:35], v[182:185], v[198:201], v[32:35]
	v_mfma_f32_16x16x32_bf16 v[20:23], v[172:175], v[206:209], v[20:23]
	v_mfma_f32_16x16x32_bf16 v[16:19], v[182:185], v[206:209], v[16:19]
	v_mfma_f32_16x16x32_bf16 v[4:7], v[172:175], v[214:217], v[4:7]
	v_mfma_f32_16x16x32_bf16 v[0:3], v[182:185], v[214:217], v[0:3]
	s_barrier
	v_lshl_add_u64 v[218:219], v[222:223], 0, s[12:13]
	s_mov_b32 m0, s35
	s_nop 0
	global_load_lds_dwordx4 v[218:219], off
	v_lshl_add_u64 v[218:219], v[224:225], 0, s[12:13]
	s_mov_b32 m0, s36
	s_nop 0
	global_load_lds_dwordx4 v[218:219], off
	s_add_i32 s45, s45, 2
	s_add_u32 s43, s43, 0x100
	s_addc_u32 s44, s44, 0
	s_cmp_gt_u32 s45, 41
	s_mov_b64 s[18:19], s[20:21]
	s_cbranch_scc0 .LBB0_1461
	s_and_b64 vcc, exec, s[14:15]
	s_cbranch_vccz .LBB0_1464
	s_barrier
